# v81 + K-loop back-edge rotation: exit test and branch moved in front of the loop-back barrier, which becomes the loop head (7.11)
# baseline (speedup 1.0000x reference)
.LBB0_267:
	s_barrier
	s_add_i32 m0, s7, 0xc000
	ds_read_b128 v[160:163], v151
	ds_read_b128 v[164:167], v151 offset:1024
	ds_read_b128 v[168:171], v151 offset:2048
	ds_read_b128 v[172:175], v151 offset:3072
	ds_read_b128 v[176:179], v151 offset:4096
	ds_read_b128 v[180:183], v151 offset:5120
	ds_read_b128 v[184:187], v151 offset:6144
	global_load_lds_dwordx4 v138, s[4:5]
	s_add_i32 m0, s7, 0xe000
	ds_read_b128 v[190:193], v151 offset:7168
	global_load_lds_dwordx4 v140, s[4:5]
	s_waitcnt lgkmcnt(8)
	s_barrier
	s_waitcnt lgkmcnt(0)
	v_mfma_f32_16x16x32_bf16 v[126:129], v[142:145], v[160:163], v[126:129]
	v_mfma_f32_16x16x32_bf16 v[122:125], v[152:155], v[160:163], v[122:125]
	v_mfma_f32_16x16x32_bf16 v[110:113], v[142:145], v[168:171], v[110:113]
	v_mfma_f32_16x16x32_bf16 v[106:109], v[152:155], v[168:171], v[106:109]
	v_mfma_f32_16x16x32_bf16 v[94:97], v[142:145], v[176:179], v[94:97]
	v_mfma_f32_16x16x32_bf16 v[90:93], v[152:155], v[176:179], v[90:93]
	v_mfma_f32_16x16x32_bf16 v[78:81], v[142:145], v[184:187], v[78:81]
	v_mfma_f32_16x16x32_bf16 v[74:77], v[152:155], v[184:187], v[74:77]
	v_mfma_f32_16x16x32_bf16 v[126:129], v[146:149], v[164:167], v[126:129]
	v_mfma_f32_16x16x32_bf16 v[122:125], v[156:159], v[164:167], v[122:125]
	v_mfma_f32_16x16x32_bf16 v[110:113], v[146:149], v[172:175], v[110:113]
	v_mfma_f32_16x16x32_bf16 v[106:109], v[156:159], v[172:175], v[106:109]
	v_mfma_f32_16x16x32_bf16 v[94:97], v[146:149], v[180:183], v[94:97]
	v_mfma_f32_16x16x32_bf16 v[90:93], v[156:159], v[180:183], v[90:93]
	v_mfma_f32_16x16x32_bf16 v[78:81], v[146:149], v[190:193], v[78:81]
	v_mfma_f32_16x16x32_bf16 v[74:77], v[156:159], v[190:193], v[74:77]
	s_barrier
	s_add_i32 m0, s22, 0x10000
	ds_read_b128 v[194:197], v189 offset:16384
	ds_read_b128 v[198:201], v189 offset:17408
	ds_read_b128 v[202:205], v189 offset:18432
	global_load_lds_dwordx4 v134, s[12:13]
	s_add_i32 m0, s22, 0x12000
	ds_read_b128 v[206:209], v189 offset:19456
	global_load_lds_dwordx4 v130, s[12:13]
	s_barrier
	s_waitcnt lgkmcnt(0)
	v_mfma_f32_16x16x32_bf16 v[118:121], v[194:197], v[160:163], v[118:121]
	v_mfma_f32_16x16x32_bf16 v[114:117], v[202:205], v[160:163], v[114:117]
	v_mfma_f32_16x16x32_bf16 v[102:105], v[194:197], v[168:171], v[102:105]
	v_mfma_f32_16x16x32_bf16 v[98:101], v[202:205], v[168:171], v[98:101]
	v_mfma_f32_16x16x32_bf16 v[86:89], v[194:197], v[176:179], v[86:89]
	v_mfma_f32_16x16x32_bf16 v[82:85], v[202:205], v[176:179], v[82:85]
	v_mfma_f32_16x16x32_bf16 v[70:73], v[194:197], v[184:187], v[70:73]
	v_mfma_f32_16x16x32_bf16 v[66:69], v[202:205], v[184:187], v[66:69]
	v_mfma_f32_16x16x32_bf16 v[118:121], v[198:201], v[164:167], v[118:121]
	v_mfma_f32_16x16x32_bf16 v[114:117], v[206:209], v[164:167], v[114:117]
	v_mfma_f32_16x16x32_bf16 v[102:105], v[198:201], v[172:175], v[102:105]
	v_mfma_f32_16x16x32_bf16 v[98:101], v[206:209], v[172:175], v[98:101]
	v_mfma_f32_16x16x32_bf16 v[86:89], v[198:201], v[180:183], v[86:89]
	v_mfma_f32_16x16x32_bf16 v[82:85], v[206:209], v[180:183], v[82:85]
	v_mfma_f32_16x16x32_bf16 v[70:73], v[198:201], v[190:193], v[70:73]
	v_mfma_f32_16x16x32_bf16 v[66:69], v[206:209], v[190:193], v[66:69]
	s_mov_b32 m0, s7
	s_mov_b64 s[100:101], s[14:15]
	s_barrier
	ds_read_b128 v[160:163], v151 offset:16384
	ds_read_b128 v[164:167], v151 offset:17408
	ds_read_b128 v[168:171], v151 offset:18432
	ds_read_b128 v[172:175], v151 offset:19456
	ds_read_b128 v[176:179], v151 offset:20480
	ds_read_b128 v[180:183], v151 offset:21504
	ds_read_b128 v[184:187], v151 offset:22528
	global_load_lds_dwordx4 v136, s[100:101]
	s_mov_b32 m0, s23
	ds_read_b128 v[190:193], v151 offset:23552
	global_load_lds_dwordx4 v132, s[100:101]
	s_waitcnt vmcnt(10)
	s_barrier
	s_waitcnt lgkmcnt(0)
	v_mfma_f32_16x16x32_bf16 v[62:65], v[142:145], v[160:163], v[62:65]
	v_mfma_f32_16x16x32_bf16 v[58:61], v[152:155], v[160:163], v[58:61]
	v_mfma_f32_16x16x32_bf16 v[46:49], v[142:145], v[168:171], v[46:49]
	v_mfma_f32_16x16x32_bf16 v[42:45], v[152:155], v[168:171], v[42:45]
	v_mfma_f32_16x16x32_bf16 v[30:33], v[142:145], v[176:179], v[30:33]
	v_mfma_f32_16x16x32_bf16 v[26:29], v[152:155], v[176:179], v[26:29]
	v_mfma_f32_16x16x32_bf16 v[14:17], v[142:145], v[184:187], v[14:17]
	v_mfma_f32_16x16x32_bf16 v[10:13], v[152:155], v[184:187], v[10:13]
	v_mfma_f32_16x16x32_bf16 v[62:65], v[146:149], v[164:167], v[62:65]
	v_mfma_f32_16x16x32_bf16 v[58:61], v[156:159], v[164:167], v[58:61]
	v_mfma_f32_16x16x32_bf16 v[46:49], v[146:149], v[172:175], v[46:49]
	v_mfma_f32_16x16x32_bf16 v[42:45], v[156:159], v[172:175], v[42:45]
	v_mfma_f32_16x16x32_bf16 v[30:33], v[146:149], v[180:183], v[30:33]
	v_mfma_f32_16x16x32_bf16 v[26:29], v[156:159], v[180:183], v[26:29]
	v_mfma_f32_16x16x32_bf16 v[14:17], v[146:149], v[190:193], v[14:17]
	v_mfma_f32_16x16x32_bf16 v[10:13], v[156:159], v[190:193], v[10:13]
	s_barrier
	s_add_u32 s86, s12, 0x40000
	s_addc_u32 s87, s13, 0
	s_add_i32 m0, s22, 0x14000
	s_nop 0
	global_load_lds_dwordx4 v134, s[86:87]
	s_add_i32 m0, s22, 0x16000
	s_nop 0
	global_load_lds_dwordx4 v130, s[86:87]
	ds_read_b128 v[142:145], v189 offset:32768
	ds_read_b128 v[146:149], v189 offset:33792
	ds_read_b128 v[152:155], v189 offset:34816
	ds_read_b128 v[156:159], v189 offset:35840
	s_waitcnt vmcnt(6)
	s_barrier
	v_mfma_f32_16x16x32_bf16 v[54:57], v[194:197], v[160:163], v[54:57]
	v_mfma_f32_16x16x32_bf16 v[50:53], v[202:205], v[160:163], v[50:53]
	v_mfma_f32_16x16x32_bf16 v[38:41], v[194:197], v[168:171], v[38:41]
	v_mfma_f32_16x16x32_bf16 v[34:37], v[202:205], v[168:171], v[34:37]
	v_mfma_f32_16x16x32_bf16 v[22:25], v[194:197], v[176:179], v[22:25]
	v_mfma_f32_16x16x32_bf16 v[18:21], v[202:205], v[176:179], v[18:21]
	v_mfma_f32_16x16x32_bf16 v[6:9], v[194:197], v[184:187], v[6:9]
	v_mfma_f32_16x16x32_bf16 v[2:5], v[202:205], v[184:187], v[2:5]
	v_mfma_f32_16x16x32_bf16 v[54:57], v[198:201], v[164:167], v[54:57]
	v_mfma_f32_16x16x32_bf16 v[50:53], v[206:209], v[164:167], v[50:53]
	v_mfma_f32_16x16x32_bf16 v[38:41], v[198:201], v[172:175], v[38:41]
	v_mfma_f32_16x16x32_bf16 v[34:37], v[206:209], v[172:175], v[34:37]
	v_mfma_f32_16x16x32_bf16 v[22:25], v[198:201], v[180:183], v[22:25]
	v_mfma_f32_16x16x32_bf16 v[18:21], v[206:209], v[180:183], v[18:21]
	v_mfma_f32_16x16x32_bf16 v[6:9], v[198:201], v[190:193], v[6:9]
	v_mfma_f32_16x16x32_bf16 v[2:5], v[206:209], v[190:193], v[2:5]
	s_barrier
	s_add_u32 s14, s14, 0x40000
	s_addc_u32 s15, s15, 0
	s_mov_b32 m0, s28
	ds_read_b128 v[160:163], v151 offset:32768
	ds_read_b128 v[164:167], v151 offset:33792
	ds_read_b128 v[168:171], v151 offset:34816
	ds_read_b128 v[172:175], v151 offset:35840
	ds_read_b128 v[176:179], v151 offset:36864
	ds_read_b128 v[180:183], v151 offset:37888
	ds_read_b128 v[184:187], v151 offset:38912
	global_load_lds_dwordx4 v136, s[14:15]
	s_mov_b32 m0, s29
	ds_read_b128 v[190:193], v151 offset:39936
	global_load_lds_dwordx4 v132, s[14:15]
	s_waitcnt lgkmcnt(8)
	s_barrier
	s_waitcnt lgkmcnt(0)
	v_mfma_f32_16x16x32_bf16 v[126:129], v[142:145], v[160:163], v[126:129]
	v_mfma_f32_16x16x32_bf16 v[122:125], v[152:155], v[160:163], v[122:125]
	v_mfma_f32_16x16x32_bf16 v[110:113], v[142:145], v[168:171], v[110:113]
	v_mfma_f32_16x16x32_bf16 v[106:109], v[152:155], v[168:171], v[106:109]
	v_mfma_f32_16x16x32_bf16 v[94:97], v[142:145], v[176:179], v[94:97]
	v_mfma_f32_16x16x32_bf16 v[90:93], v[152:155], v[176:179], v[90:93]
	v_mfma_f32_16x16x32_bf16 v[78:81], v[142:145], v[184:187], v[78:81]
	v_mfma_f32_16x16x32_bf16 v[74:77], v[152:155], v[184:187], v[74:77]
	v_mfma_f32_16x16x32_bf16 v[126:129], v[146:149], v[164:167], v[126:129]
	v_mfma_f32_16x16x32_bf16 v[122:125], v[156:159], v[164:167], v[122:125]
	v_mfma_f32_16x16x32_bf16 v[110:113], v[146:149], v[172:175], v[110:113]
	v_mfma_f32_16x16x32_bf16 v[106:109], v[156:159], v[172:175], v[106:109]
	v_mfma_f32_16x16x32_bf16 v[94:97], v[146:149], v[180:183], v[94:97]
	v_mfma_f32_16x16x32_bf16 v[90:93], v[156:159], v[180:183], v[90:93]
	v_mfma_f32_16x16x32_bf16 v[78:81], v[146:149], v[190:193], v[78:81]
	v_mfma_f32_16x16x32_bf16 v[74:77], v[156:159], v[190:193], v[74:77]
	s_barrier
	s_add_i32 m0, s22, 0x18000
	ds_read_b128 v[194:197], v189 offset:49152
	ds_read_b128 v[198:201], v189 offset:50176
	ds_read_b128 v[202:205], v189 offset:51200
	ds_read_b128 v[206:209], v189 offset:52224
	s_add_u32 s98, s12, s40
	s_addc_u32 s99, s13, s41
	global_load_lds_dwordx4 v134, s[98:99]
	s_add_i32 m0, s22, 0x1a000
	s_nop 0
	global_load_lds_dwordx4 v130, s[98:99]
	s_barrier
	s_waitcnt lgkmcnt(0)
	v_mfma_f32_16x16x32_bf16 v[118:121], v[194:197], v[160:163], v[118:121]
	v_mfma_f32_16x16x32_bf16 v[114:117], v[202:205], v[160:163], v[114:117]
	v_mfma_f32_16x16x32_bf16 v[102:105], v[194:197], v[168:171], v[102:105]
	v_mfma_f32_16x16x32_bf16 v[98:101], v[202:205], v[168:171], v[98:101]
	v_mfma_f32_16x16x32_bf16 v[86:89], v[194:197], v[176:179], v[86:89]
	v_mfma_f32_16x16x32_bf16 v[82:85], v[202:205], v[176:179], v[82:85]
	v_mfma_f32_16x16x32_bf16 v[70:73], v[194:197], v[184:187], v[70:73]
	v_mfma_f32_16x16x32_bf16 v[66:69], v[202:205], v[184:187], v[66:69]
	v_mfma_f32_16x16x32_bf16 v[118:121], v[198:201], v[164:167], v[118:121]
	v_mfma_f32_16x16x32_bf16 v[114:117], v[206:209], v[164:167], v[114:117]
	v_mfma_f32_16x16x32_bf16 v[102:105], v[198:201], v[172:175], v[102:105]
	v_mfma_f32_16x16x32_bf16 v[98:101], v[206:209], v[172:175], v[98:101]
	v_mfma_f32_16x16x32_bf16 v[86:89], v[198:201], v[180:183], v[86:89]
	v_mfma_f32_16x16x32_bf16 v[82:85], v[206:209], v[180:183], v[82:85]
	v_mfma_f32_16x16x32_bf16 v[70:73], v[198:201], v[190:193], v[70:73]
	v_mfma_f32_16x16x32_bf16 v[66:69], v[206:209], v[190:193], v[66:69]
	s_mov_b32 m0, s38
	s_barrier
	ds_read_b128 v[160:163], v151 offset:49152
	ds_read_b128 v[164:167], v151 offset:50176
	ds_read_b128 v[168:171], v151 offset:51200
	ds_read_b128 v[172:175], v151 offset:52224
	ds_read_b128 v[176:179], v151 offset:53248
	ds_read_b128 v[180:183], v151 offset:54272
	ds_read_b128 v[184:187], v151 offset:55296
	ds_read_b128 v[190:193], v151 offset:56320
	s_add_u32 s98, s100, s40
	s_addc_u32 s99, s101, s41
	global_load_lds_dwordx4 v136, s[98:99]
	s_mov_b32 m0, s39
	s_nop 0
	global_load_lds_dwordx4 v132, s[98:99]
	s_waitcnt vmcnt(10)
	s_barrier
	s_waitcnt lgkmcnt(0)
	v_mfma_f32_16x16x32_bf16 v[62:65], v[142:145], v[160:163], v[62:65]
	v_mfma_f32_16x16x32_bf16 v[58:61], v[152:155], v[160:163], v[58:61]
	v_mfma_f32_16x16x32_bf16 v[46:49], v[142:145], v[168:171], v[46:49]
	v_mfma_f32_16x16x32_bf16 v[42:45], v[152:155], v[168:171], v[42:45]
	v_mfma_f32_16x16x32_bf16 v[30:33], v[142:145], v[176:179], v[30:33]
	v_mfma_f32_16x16x32_bf16 v[26:29], v[152:155], v[176:179], v[26:29]
	v_mfma_f32_16x16x32_bf16 v[14:17], v[142:145], v[184:187], v[14:17]
	v_mfma_f32_16x16x32_bf16 v[10:13], v[152:155], v[184:187], v[10:13]
	v_mfma_f32_16x16x32_bf16 v[62:65], v[146:149], v[164:167], v[62:65]
	v_mfma_f32_16x16x32_bf16 v[58:61], v[156:159], v[164:167], v[58:61]
	v_mfma_f32_16x16x32_bf16 v[46:49], v[146:149], v[172:175], v[46:49]
	v_mfma_f32_16x16x32_bf16 v[42:45], v[156:159], v[172:175], v[42:45]
	v_mfma_f32_16x16x32_bf16 v[30:33], v[146:149], v[180:183], v[30:33]
	v_mfma_f32_16x16x32_bf16 v[26:29], v[156:159], v[180:183], v[26:29]
	v_mfma_f32_16x16x32_bf16 v[14:17], v[146:149], v[190:193], v[14:17]
	v_mfma_f32_16x16x32_bf16 v[10:13], v[156:159], v[190:193], v[10:13]
	s_barrier
	s_add_u32 s12, s12, 0x40080
	s_addc_u32 s13, s13, 0
	s_add_i32 m0, s22, 0x1c000
	s_nop 0
	global_load_lds_dwordx4 v134, s[12:13]
	s_add_i32 m0, s22, 0x1e000
	s_nop 0
	global_load_lds_dwordx4 v130, s[12:13]
	ds_read_b128 v[142:145], v189
	ds_read_b128 v[146:149], v189 offset:1024
	ds_read_b128 v[152:155], v189 offset:2048
	ds_read_b128 v[156:159], v189 offset:3072
	s_waitcnt vmcnt(6)
	s_barrier
	v_mfma_f32_16x16x32_bf16 v[54:57], v[194:197], v[160:163], v[54:57]
	v_mfma_f32_16x16x32_bf16 v[50:53], v[202:205], v[160:163], v[50:53]
	v_mfma_f32_16x16x32_bf16 v[38:41], v[194:197], v[168:171], v[38:41]
	v_mfma_f32_16x16x32_bf16 v[34:37], v[202:205], v[168:171], v[34:37]
	v_mfma_f32_16x16x32_bf16 v[22:25], v[194:197], v[176:179], v[22:25]
	v_mfma_f32_16x16x32_bf16 v[18:21], v[202:205], v[176:179], v[18:21]
	v_mfma_f32_16x16x32_bf16 v[6:9], v[194:197], v[184:187], v[6:9]
	v_mfma_f32_16x16x32_bf16 v[2:5], v[202:205], v[184:187], v[2:5]
	v_mfma_f32_16x16x32_bf16 v[54:57], v[198:201], v[164:167], v[54:57]
	v_mfma_f32_16x16x32_bf16 v[50:53], v[206:209], v[164:167], v[50:53]
	v_mfma_f32_16x16x32_bf16 v[38:41], v[198:201], v[172:175], v[38:41]
	v_mfma_f32_16x16x32_bf16 v[34:37], v[206:209], v[172:175], v[34:37]
	v_mfma_f32_16x16x32_bf16 v[22:25], v[198:201], v[180:183], v[22:25]
	v_mfma_f32_16x16x32_bf16 v[18:21], v[206:209], v[180:183], v[18:21]
	v_mfma_f32_16x16x32_bf16 v[6:9], v[198:201], v[190:193], v[6:9]
	v_mfma_f32_16x16x32_bf16 v[2:5], v[206:209], v[190:193], v[2:5]
	s_add_i32 s85, s85, 2
	s_add_u32 s4, s4, 0x100
	s_addc_u32 s5, s5, 0
	s_add_u32 s78, s78, 0x100
	s_addc_u32 s79, s79, 0
	s_add_u32 s12, s4, 0xfffc0080
	s_addc_u32 s13, s5, -1
	s_cmp_eq_u32 s85, 12
	s_cselect_b32 s15, s44, s13
	s_cselect_b32 s14, s45, s12
	s_cselect_b32 s13, s47, s79
	s_cselect_b32 s12, s55, s78
	s_cmp_gt_u32 s85, 13
	s_cbranch_scc0 .LBB0_267
	s_barrier
	s_waitcnt lgkmcnt(0)
	v_mov_b32_e32 v156, v252
	s_mov_b64 s[4:5], -1
	v_and_b32_e32 v154, 63, v156
	s_andn2_b64 vcc, exec, s[2:3]
	v_lshlrev_b32_e32 v142, 2, v154
	s_cbranch_vccnz .LBB0_270
	v_lshlrev_b32_e32 v155, 2, v154
	s_mov_b64 s[4:5], 0

.LBB0_838:
	s_barrier
	v_lshl_add_u64 v[178:179], s[88:89], 0, v[196:197]
	s_add_i32 m0, s39, 0xc000
	ds_read_b128 v[146:149], v213
	ds_read_b128 v[150:153], v213 offset:1024
	ds_read_b128 v[154:157], v213 offset:2048
	ds_read_b128 v[158:161], v213 offset:3072
	ds_read_b128 v[162:165], v213 offset:4096
	ds_read_b128 v[166:169], v213 offset:5120
	ds_read_b128 v[170:173], v213 offset:6144
	ds_read_b128 v[174:177], v213 offset:7168
	global_load_lds_dwordx4 v[178:179], off
	s_add_i32 m0, s39, 0xe000
	v_lshl_add_u64 v[178:179], s[88:89], 0, v[198:199]
	global_load_lds_dwordx4 v[178:179], off
	s_waitcnt lgkmcnt(8)
	s_barrier
	s_waitcnt lgkmcnt(0)
	v_mfma_f32_16x16x32_bf16 v[126:129], v[130:133], v[146:149], v[126:129]
	v_mfma_f32_16x16x32_bf16 v[122:125], v[138:141], v[146:149], v[122:125]
	v_mfma_f32_16x16x32_bf16 v[110:113], v[130:133], v[154:157], v[110:113]
	v_mfma_f32_16x16x32_bf16 v[106:109], v[138:141], v[154:157], v[106:109]
	v_mfma_f32_16x16x32_bf16 v[94:97], v[130:133], v[162:165], v[94:97]
	v_mfma_f32_16x16x32_bf16 v[90:93], v[138:141], v[162:165], v[90:93]
	v_mfma_f32_16x16x32_bf16 v[78:81], v[130:133], v[170:173], v[78:81]
	v_mfma_f32_16x16x32_bf16 v[74:77], v[138:141], v[170:173], v[74:77]
	v_mfma_f32_16x16x32_bf16 v[126:129], v[134:137], v[150:153], v[126:129]
	v_mfma_f32_16x16x32_bf16 v[122:125], v[142:145], v[150:153], v[122:125]
	v_mfma_f32_16x16x32_bf16 v[110:113], v[134:137], v[158:161], v[110:113]
	v_mfma_f32_16x16x32_bf16 v[106:109], v[142:145], v[158:161], v[106:109]
	v_mfma_f32_16x16x32_bf16 v[94:97], v[134:137], v[166:169], v[94:97]
	v_mfma_f32_16x16x32_bf16 v[90:93], v[142:145], v[166:169], v[90:93]
	v_mfma_f32_16x16x32_bf16 v[78:81], v[134:137], v[174:177], v[78:81]
	v_mfma_f32_16x16x32_bf16 v[74:77], v[142:145], v[174:177], v[74:77]
	s_barrier
	ds_read_b128 v[178:181], v189 offset:16384
	ds_read_b128 v[182:185], v189 offset:17408
	ds_read_b128 v[200:203], v189 offset:18432
	ds_read_b128 v[204:207], v189 offset:19456
	s_add_i32 m0, s38, 0x10000
	s_nop 0
	global_load_lds_dwordx4 v0, s[90:91]
	s_add_i32 m0, s38, 0x12000
	s_nop 0
	global_load_lds_dwordx4 v194, s[90:91]
	s_barrier
	s_waitcnt lgkmcnt(0)
	v_mfma_f32_16x16x32_bf16 v[118:121], v[178:181], v[146:149], v[118:121]
	v_mfma_f32_16x16x32_bf16 v[114:117], v[200:203], v[146:149], v[114:117]
	v_mfma_f32_16x16x32_bf16 v[102:105], v[178:181], v[154:157], v[102:105]
	v_mfma_f32_16x16x32_bf16 v[98:101], v[200:203], v[154:157], v[98:101]
	v_mfma_f32_16x16x32_bf16 v[86:89], v[178:181], v[162:165], v[86:89]
	v_mfma_f32_16x16x32_bf16 v[82:85], v[200:203], v[162:165], v[82:85]
	v_mfma_f32_16x16x32_bf16 v[70:73], v[178:181], v[170:173], v[70:73]
	v_mfma_f32_16x16x32_bf16 v[66:69], v[200:203], v[170:173], v[66:69]
	v_mfma_f32_16x16x32_bf16 v[118:121], v[182:185], v[150:153], v[118:121]
	v_mfma_f32_16x16x32_bf16 v[114:117], v[204:207], v[150:153], v[114:117]
	v_mfma_f32_16x16x32_bf16 v[102:105], v[182:185], v[158:161], v[102:105]
	v_mfma_f32_16x16x32_bf16 v[98:101], v[204:207], v[158:161], v[98:101]
	v_mfma_f32_16x16x32_bf16 v[86:89], v[182:185], v[166:169], v[86:89]
	v_mfma_f32_16x16x32_bf16 v[82:85], v[204:207], v[166:169], v[82:85]
	v_mfma_f32_16x16x32_bf16 v[70:73], v[182:185], v[174:177], v[70:73]
	v_mfma_f32_16x16x32_bf16 v[66:69], v[204:207], v[174:177], v[66:69]
	s_mov_b32 m0, s39
	s_barrier
	ds_read_b128 v[146:149], v213 offset:16384
	ds_read_b128 v[150:153], v213 offset:17408
	ds_read_b128 v[154:157], v213 offset:18432
	ds_read_b128 v[158:161], v213 offset:19456
	ds_read_b128 v[162:165], v213 offset:20480
	ds_read_b128 v[166:169], v213 offset:21504
	ds_read_b128 v[170:173], v213 offset:22528
	global_load_lds_dwordx4 v190, s[92:93]
	s_mov_b32 m0, s42
	ds_read_b128 v[174:177], v213 offset:23552
	global_load_lds_dwordx4 v192, s[92:93]
	s_waitcnt vmcnt(10)
	s_barrier
	s_waitcnt lgkmcnt(0)
	v_mfma_f32_16x16x32_bf16 v[62:65], v[130:133], v[146:149], v[62:65]
	v_mfma_f32_16x16x32_bf16 v[58:61], v[138:141], v[146:149], v[58:61]
	v_mfma_f32_16x16x32_bf16 v[46:49], v[130:133], v[154:157], v[46:49]
	v_mfma_f32_16x16x32_bf16 v[42:45], v[138:141], v[154:157], v[42:45]
	v_mfma_f32_16x16x32_bf16 v[30:33], v[130:133], v[162:165], v[30:33]
	v_mfma_f32_16x16x32_bf16 v[26:29], v[138:141], v[162:165], v[26:29]
	v_mfma_f32_16x16x32_bf16 v[14:17], v[130:133], v[170:173], v[14:17]
	v_mfma_f32_16x16x32_bf16 v[10:13], v[138:141], v[170:173], v[10:13]
	v_mfma_f32_16x16x32_bf16 v[62:65], v[134:137], v[150:153], v[62:65]
	v_mfma_f32_16x16x32_bf16 v[58:61], v[142:145], v[150:153], v[58:61]
	v_mfma_f32_16x16x32_bf16 v[46:49], v[134:137], v[158:161], v[46:49]
	v_mfma_f32_16x16x32_bf16 v[42:45], v[142:145], v[158:161], v[42:45]
	v_mfma_f32_16x16x32_bf16 v[30:33], v[134:137], v[166:169], v[30:33]
	v_mfma_f32_16x16x32_bf16 v[26:29], v[142:145], v[166:169], v[26:29]
	v_mfma_f32_16x16x32_bf16 v[14:17], v[134:137], v[174:177], v[14:17]
	v_mfma_f32_16x16x32_bf16 v[10:13], v[142:145], v[174:177], v[10:13]
	s_barrier
	s_add_u32 s88, s90, 0x40000
	s_addc_u32 s89, s91, 0
	s_add_i32 m0, s38, 0x14000
	s_nop 0
	global_load_lds_dwordx4 v0, s[88:89]
	s_add_i32 m0, s38, 0x16000
	s_nop 0
	global_load_lds_dwordx4 v194, s[88:89]
	s_add_i32 s79, 0, 0x18000
	v_add_u32_e32 v142, s79, v212
	ds_read_b128 v[130:133], v142
	ds_read_b128 v[134:137], v142 offset:1024
	ds_read_b128 v[138:141], v142 offset:2048
	ds_read_b128 v[142:145], v142 offset:3072
	s_waitcnt vmcnt(6)
	s_barrier
	v_mfma_f32_16x16x32_bf16 v[54:57], v[178:181], v[146:149], v[54:57]
	v_mfma_f32_16x16x32_bf16 v[50:53], v[200:203], v[146:149], v[50:53]
	v_mfma_f32_16x16x32_bf16 v[38:41], v[178:181], v[154:157], v[38:41]
	v_mfma_f32_16x16x32_bf16 v[34:37], v[200:203], v[154:157], v[34:37]
	v_mfma_f32_16x16x32_bf16 v[22:25], v[178:181], v[162:165], v[22:25]
	v_mfma_f32_16x16x32_bf16 v[18:21], v[200:203], v[162:165], v[18:21]
	v_mfma_f32_16x16x32_bf16 v[6:9], v[178:181], v[170:173], v[6:9]
	v_mfma_f32_16x16x32_bf16 v[2:5], v[200:203], v[170:173], v[2:5]
	v_mfma_f32_16x16x32_bf16 v[54:57], v[182:185], v[150:153], v[54:57]
	v_mfma_f32_16x16x32_bf16 v[50:53], v[204:207], v[150:153], v[50:53]
	v_mfma_f32_16x16x32_bf16 v[38:41], v[182:185], v[158:161], v[38:41]
	v_mfma_f32_16x16x32_bf16 v[34:37], v[204:207], v[158:161], v[34:37]
	v_mfma_f32_16x16x32_bf16 v[22:25], v[182:185], v[166:169], v[22:25]
	v_mfma_f32_16x16x32_bf16 v[18:21], v[204:207], v[166:169], v[18:21]
	v_mfma_f32_16x16x32_bf16 v[6:9], v[182:185], v[174:177], v[6:9]
	v_mfma_f32_16x16x32_bf16 v[2:5], v[204:207], v[174:177], v[2:5]
	s_barrier
	s_add_u32 s88, s92, 0xc0000
	s_addc_u32 s89, s93, 0
	s_mov_b32 m0, s43
	ds_read_b128 v[146:149], v213 offset:32768
	ds_read_b128 v[150:153], v213 offset:33792
	ds_read_b128 v[154:157], v213 offset:34816
	ds_read_b128 v[158:161], v213 offset:35840
	ds_read_b128 v[162:165], v213 offset:36864
	ds_read_b128 v[166:169], v213 offset:37888
	ds_read_b128 v[170:173], v213 offset:38912
	global_load_lds_dwordx4 v190, s[88:89]
	s_mov_b32 m0, s44
	ds_read_b128 v[174:177], v213 offset:39936
	global_load_lds_dwordx4 v192, s[88:89]
	s_waitcnt lgkmcnt(8)
	s_barrier
	s_waitcnt lgkmcnt(0)
	v_mfma_f32_16x16x32_bf16 v[126:129], v[130:133], v[146:149], v[126:129]
	v_mfma_f32_16x16x32_bf16 v[122:125], v[138:141], v[146:149], v[122:125]
	v_mfma_f32_16x16x32_bf16 v[110:113], v[130:133], v[154:157], v[110:113]
	v_mfma_f32_16x16x32_bf16 v[106:109], v[138:141], v[154:157], v[106:109]
	v_mfma_f32_16x16x32_bf16 v[94:97], v[130:133], v[162:165], v[94:97]
	v_mfma_f32_16x16x32_bf16 v[90:93], v[138:141], v[162:165], v[90:93]
	v_mfma_f32_16x16x32_bf16 v[78:81], v[130:133], v[170:173], v[78:81]
	v_mfma_f32_16x16x32_bf16 v[74:77], v[138:141], v[170:173], v[74:77]
	v_mfma_f32_16x16x32_bf16 v[126:129], v[134:137], v[150:153], v[126:129]
	v_mfma_f32_16x16x32_bf16 v[122:125], v[142:145], v[150:153], v[122:125]
	v_mfma_f32_16x16x32_bf16 v[110:113], v[134:137], v[158:161], v[110:113]
	v_mfma_f32_16x16x32_bf16 v[106:109], v[142:145], v[158:161], v[106:109]
	v_mfma_f32_16x16x32_bf16 v[94:97], v[134:137], v[166:169], v[94:97]
	v_mfma_f32_16x16x32_bf16 v[90:93], v[142:145], v[166:169], v[90:93]
	v_mfma_f32_16x16x32_bf16 v[78:81], v[134:137], v[174:177], v[78:81]
	v_mfma_f32_16x16x32_bf16 v[74:77], v[142:145], v[174:177], v[74:77]
	s_barrier
	s_add_i32 s87, 0, 0x1c000
	v_add_u32_e32 v204, s87, v212
	s_add_i32 m0, s38, 0x18000
	ds_read_b128 v[178:181], v204
	ds_read_b128 v[182:185], v204 offset:1024
	ds_read_b128 v[200:203], v204 offset:2048
	ds_read_b128 v[204:207], v204 offset:3072
	s_add_u32 s98, s90, s40
	s_addc_u32 s99, s91, s41
	global_load_lds_dwordx4 v0, s[98:99]
	s_add_i32 m0, s38, 0x1a000
	s_nop 0
	global_load_lds_dwordx4 v194, s[98:99]
	s_barrier
	s_waitcnt lgkmcnt(0)
	v_mfma_f32_16x16x32_bf16 v[118:121], v[178:181], v[146:149], v[118:121]
	v_mfma_f32_16x16x32_bf16 v[114:117], v[200:203], v[146:149], v[114:117]
	v_mfma_f32_16x16x32_bf16 v[102:105], v[178:181], v[154:157], v[102:105]
	v_mfma_f32_16x16x32_bf16 v[98:101], v[200:203], v[154:157], v[98:101]
	v_mfma_f32_16x16x32_bf16 v[86:89], v[178:181], v[162:165], v[86:89]
	v_mfma_f32_16x16x32_bf16 v[82:85], v[200:203], v[162:165], v[82:85]
	v_mfma_f32_16x16x32_bf16 v[70:73], v[178:181], v[170:173], v[70:73]
	v_mfma_f32_16x16x32_bf16 v[66:69], v[200:203], v[170:173], v[66:69]
	v_mfma_f32_16x16x32_bf16 v[118:121], v[182:185], v[150:153], v[118:121]
	v_mfma_f32_16x16x32_bf16 v[114:117], v[204:207], v[150:153], v[114:117]
	v_mfma_f32_16x16x32_bf16 v[102:105], v[182:185], v[158:161], v[102:105]
	v_mfma_f32_16x16x32_bf16 v[98:101], v[204:207], v[158:161], v[98:101]
	v_mfma_f32_16x16x32_bf16 v[86:89], v[182:185], v[166:169], v[86:89]
	v_mfma_f32_16x16x32_bf16 v[82:85], v[204:207], v[166:169], v[82:85]
	v_mfma_f32_16x16x32_bf16 v[70:73], v[182:185], v[174:177], v[70:73]
	v_mfma_f32_16x16x32_bf16 v[66:69], v[204:207], v[174:177], v[66:69]
	s_mov_b32 m0, s60
	s_barrier
	ds_read_b128 v[146:149], v213 offset:49152
	ds_read_b128 v[150:153], v213 offset:50176
	ds_read_b128 v[154:157], v213 offset:51200
	ds_read_b128 v[158:161], v213 offset:52224
	ds_read_b128 v[162:165], v213 offset:53248
	ds_read_b128 v[166:169], v213 offset:54272
	ds_read_b128 v[170:173], v213 offset:55296
	ds_read_b128 v[174:177], v213 offset:56320
	s_add_u32 s98, s92, s40
	s_addc_u32 s99, s93, s41
	global_load_lds_dwordx4 v190, s[98:99]
	s_mov_b32 m0, s61
	s_nop 0
	global_load_lds_dwordx4 v192, s[98:99]
	s_waitcnt vmcnt(10)
	s_barrier
	s_waitcnt lgkmcnt(0)
	v_mfma_f32_16x16x32_bf16 v[62:65], v[130:133], v[146:149], v[62:65]
	v_mfma_f32_16x16x32_bf16 v[58:61], v[138:141], v[146:149], v[58:61]
	v_mfma_f32_16x16x32_bf16 v[46:49], v[130:133], v[154:157], v[46:49]
	v_mfma_f32_16x16x32_bf16 v[42:45], v[138:141], v[154:157], v[42:45]
	v_mfma_f32_16x16x32_bf16 v[30:33], v[130:133], v[162:165], v[30:33]
	v_mfma_f32_16x16x32_bf16 v[26:29], v[138:141], v[162:165], v[26:29]
	v_mfma_f32_16x16x32_bf16 v[14:17], v[130:133], v[170:173], v[14:17]
	v_mfma_f32_16x16x32_bf16 v[10:13], v[138:141], v[170:173], v[10:13]
	v_mfma_f32_16x16x32_bf16 v[62:65], v[134:137], v[150:153], v[62:65]
	v_mfma_f32_16x16x32_bf16 v[58:61], v[142:145], v[150:153], v[58:61]
	v_mfma_f32_16x16x32_bf16 v[46:49], v[134:137], v[158:161], v[46:49]
	v_mfma_f32_16x16x32_bf16 v[42:45], v[142:145], v[158:161], v[42:45]
	v_mfma_f32_16x16x32_bf16 v[30:33], v[134:137], v[166:169], v[30:33]
	v_mfma_f32_16x16x32_bf16 v[26:29], v[142:145], v[166:169], v[26:29]
	v_mfma_f32_16x16x32_bf16 v[14:17], v[134:137], v[174:177], v[14:17]
	v_mfma_f32_16x16x32_bf16 v[10:13], v[142:145], v[174:177], v[10:13]
	s_barrier
	s_add_u32 s88, s90, 0x40080
	s_addc_u32 s89, s91, 0
	s_add_i32 m0, s38, 0x1c000
	s_nop 0
	global_load_lds_dwordx4 v0, s[88:89]
	s_add_i32 m0, s38, 0x1e000
	s_nop 0
	global_load_lds_dwordx4 v194, s[88:89]
	ds_read_b128 v[130:133], v189
	ds_read_b128 v[134:137], v189 offset:1024
	ds_read_b128 v[138:141], v189 offset:2048
	ds_read_b128 v[142:145], v189 offset:3072
	s_waitcnt vmcnt(6)
	s_barrier
	v_mfma_f32_16x16x32_bf16 v[54:57], v[178:181], v[146:149], v[54:57]
	v_mfma_f32_16x16x32_bf16 v[50:53], v[200:203], v[146:149], v[50:53]
	v_mfma_f32_16x16x32_bf16 v[38:41], v[178:181], v[154:157], v[38:41]
	v_mfma_f32_16x16x32_bf16 v[34:37], v[200:203], v[154:157], v[34:37]
	v_mfma_f32_16x16x32_bf16 v[22:25], v[178:181], v[162:165], v[22:25]
	v_mfma_f32_16x16x32_bf16 v[18:21], v[200:203], v[162:165], v[18:21]
	v_mfma_f32_16x16x32_bf16 v[6:9], v[178:181], v[170:173], v[6:9]
	v_mfma_f32_16x16x32_bf16 v[2:5], v[200:203], v[170:173], v[2:5]
	v_mfma_f32_16x16x32_bf16 v[54:57], v[182:185], v[150:153], v[54:57]
	v_mfma_f32_16x16x32_bf16 v[50:53], v[204:207], v[150:153], v[50:53]
	v_mfma_f32_16x16x32_bf16 v[38:41], v[182:185], v[158:161], v[38:41]
	v_mfma_f32_16x16x32_bf16 v[34:37], v[204:207], v[158:161], v[34:37]
	v_mfma_f32_16x16x32_bf16 v[22:25], v[182:185], v[166:169], v[22:25]
	v_mfma_f32_16x16x32_bf16 v[18:21], v[204:207], v[166:169], v[18:21]
	v_mfma_f32_16x16x32_bf16 v[6:9], v[182:185], v[174:177], v[6:9]
	v_mfma_f32_16x16x32_bf16 v[2:5], v[204:207], v[174:177], v[2:5]
	s_add_i32 s78, s78, 2
	s_add_u32 s34, s34, 0x100
	s_addc_u32 s75, s75, 0
	s_mov_b64 s[88:89], s[4:5]
	s_add_u32 s4, s88, 0x100
	s_addc_u32 s5, s89, 0
	s_cmp_eq_u32 s78, 12
	s_cselect_b32 s93, s17, s5
	s_cselect_b32 s92, s16, s4
	s_cselect_b32 s91, s15, s75
	s_cselect_b32 s90, s23, s34
	s_cmp_gt_u32 s78, 13
	s_cbranch_scc0 .LBB0_838
	s_barrier
	s_waitcnt lgkmcnt(0)
	s_lshl_b32 s4, s22, 8
	v_mov_b32_e32 v186, v252
	s_add_i32 s4, s4, s47
	s_nop 0
	v_and_or_b32 v202, v186, 15, s4
	s_lshl_b32 s4, s86, 8
	s_or_b32 s4, s4, s55
	v_lshrrev_b32_e32 v130, 1, v186
	v_and_or_b32 v200, v130, 24, s4
	v_ashrrev_i32_e32 v201, 31, v200
	v_ashrrev_i32_e32 v203, 31, v202
	v_lshl_add_u64 v[204:205], v[200:201], 2, s[6:7]
	v_lshlrev_b64 v[130:131], 12, v[202:203]
	v_lshl_add_u64 v[130:131], v[204:205], 0, v[130:131]
	global_load_dwordx4 v[216:219], v[130:131], off offset:16
	global_load_dwordx4 v[220:223], v[130:131], off
	global_load_dwordx4 v[178:181], v[130:131], off offset:528
	global_load_dwordx4 v[182:185], v[130:131], off offset:512
	v_or_b32_e32 v210, 16, v202
	v_ashrrev_i32_e32 v211, 31, v210
	v_lshlrev_b64 v[130:131], 12, v[210:211]
	v_or_b32_e32 v208, 32, v202
	v_lshl_add_u64 v[130:131], v[204:205], 0, v[130:131]
	v_ashrrev_i32_e32 v209, 31, v208
	global_load_dwordx4 v[170:173], v[130:131], off offset:16
	global_load_dwordx4 v[174:177], v[130:131], off
	global_load_dwordx4 v[162:165], v[130:131], off offset:528
	global_load_dwordx4 v[166:169], v[130:131], off offset:512
	v_lshlrev_b64 v[130:131], 12, v[208:209]
	v_or_b32_e32 v206, 48, v202
	v_lshl_add_u64 v[130:131], v[204:205], 0, v[130:131]
	v_ashrrev_i32_e32 v207, 31, v206
	global_load_dwordx4 v[154:157], v[130:131], off offset:16
	global_load_dwordx4 v[158:161], v[130:131], off
	global_load_dwordx4 v[138:141], v[130:131], off offset:528
	global_load_dwordx4 v[142:145], v[130:131], off offset:512
	v_lshlrev_b64 v[130:131], 12, v[206:207]
	v_lshl_add_u64 v[134:135], v[204:205], 0, v[130:131]
	global_load_dwordx4 v[146:149], v[134:135], off offset:16
	global_load_dwordx4 v[150:153], v[134:135], off
	global_load_dwordx4 v[130:133], v[134:135], off offset:528
	s_nop 0
	global_load_dwordx4 v[134:137], v[134:135], off offset:512
	v_and_b32_e32 v186, 63, v186
	v_lshlrev_b32_e32 v187, 2, v186
	v_xor_b32_e32 v215, 64, v187
	v_xor_b32_e32 v214, 0x80, v187
	v_cmp_gt_u32_e32 vcc, 16, v186
	v_lshlrev_b64 v[186:187], 10, v[202:203]
	v_lshl_add_u64 v[186:187], v[186:187], 0, v[200:201]
	s_lshl_b32 s4, s86, 2
	s_ashr_i32 s5, s4, 31
	s_waitcnt vmcnt(0)
	v_pk_add_f32 v[124:125], v[124:125], v[218:219]
	v_pk_add_f32 v[128:129], v[128:129], v[222:223]
	v_pk_add_f32 v[126:127], v[126:127], v[220:221]
	v_pk_mul_f32 v[218:219], v[128:129], v[128:129]
	v_pk_mul_f32 v[220:221], v[126:127], v[126:127]
	v_pk_add_f32 v[122:123], v[122:123], v[216:217]
	v_lshl_add_u64 v[216:217], v[186:187], 2, s[12:13]
	v_add_f32_e32 v220, v220, v221
	v_add_f32_e32 v218, v218, v219
	global_store_dwordx4 v[216:217], v[126:129], off
	global_store_dwordx4 v[216:217], v[122:125], off offset:16
	v_add_f32_e32 v222, v220, v218
	v_pk_mul_f32 v[220:221], v[122:123], v[122:123]
	v_cvt_pk_bf16_f32 v126, v126, v127
	v_cvt_pk_bf16_f32 v127, v128, v129
	v_cvt_pk_bf16_f32 v128, v122, v123
	v_cvt_pk_bf16_f32 v129, v124, v125
	v_lshl_add_u64 v[122:123], v[186:187], 1, s[8:9]
	v_pk_add_f32 v[120:121], v[120:121], v[184:185]
	v_pk_add_f32 v[118:119], v[118:119], v[182:183]
	v_pk_mul_f32 v[218:219], v[124:125], v[124:125]
	global_store_dwordx4 v[122:123], v[126:129], off
	v_pk_mul_f32 v[124:125], v[120:121], v[120:121]
	v_pk_add_f32 v[116:117], v[116:117], v[180:181]
	v_pk_mul_f32 v[126:127], v[118:119], v[118:119]
	v_pk_add_f32 v[114:115], v[114:115], v[178:179]
	v_add_f32_e32 v126, v126, v127
	v_add_f32_e32 v124, v124, v125
	v_add_f32_e32 v128, v126, v124
	v_pk_mul_f32 v[124:125], v[116:117], v[116:117]
	v_pk_mul_f32 v[126:127], v[114:115], v[114:115]
	v_add_f32_e32 v220, v220, v221
	v_add_f32_e32 v218, v218, v219
	v_add_f32_e32 v126, v126, v127
	v_add_f32_e32 v124, v124, v125
	v_add_f32_e32 v218, v220, v218
	v_add_f32_e32 v124, v126, v124
	v_add_f32_e32 v218, v222, v218
	v_add_f32_e32 v124, v128, v124
	v_add_f32_e32 v124, v218, v124
	global_store_dwordx4 v[216:217], v[118:121], off offset:512
	global_store_dwordx4 v[216:217], v[114:117], off offset:528
	s_nop 0
	v_cvt_pk_bf16_f32 v118, v118, v119
	v_cvt_pk_bf16_f32 v119, v120, v121
	v_cvt_pk_bf16_f32 v120, v114, v115
	ds_bpermute_b32 v114, v215, v124
	v_cvt_pk_bf16_f32 v121, v116, v117
	global_store_dwordx4 v[122:123], v[118:121], off offset:256
	s_waitcnt lgkmcnt(0)
	v_add_f32_e32 v114, v124, v114
	ds_bpermute_b32 v115, v214, v114
	s_and_saveexec_b64 s[22:23], vcc
	s_cbranch_execz .LBB0_841
	v_lshlrev_b64 v[116:117], 6, v[202:203]
	v_lshl_add_u64 v[116:117], s[10:11], 0, v[116:117]
	v_lshl_add_u64 v[116:117], s[4:5], 2, v[116:117]
	s_lshl_b32 s34, s45, 2
	v_lshl_add_u64 v[116:117], v[116:117], 0, s[34:35]
	s_waitcnt lgkmcnt(0)
	v_add_f32_e32 v114, v114, v115
	global_store_dword v[116:117], v114, off

.LBB0_919:
	s_barrier
	s_add_i32 m0, s43, 0xc000
	ds_read_b128 v[146:149], v253
	ds_read_b128 v[150:153], v253 offset:1024
	ds_read_b128 v[168:171], v253 offset:2048
	ds_read_b128 v[172:175], v253 offset:3072
	ds_read_b128 v[176:179], v253 offset:4096
	ds_read_b128 v[180:183], v253 offset:5120
	ds_read_b128 v[184:187], v253 offset:6144
	ds_read_b128 v[190:193], v253 offset:7168
	global_load_lds_dwordx4 v164, s[6:7]
	s_add_i32 m0, s43, 0xe000
	v_lshl_add_u64 v[154:155], s[6:7], 0, v[166:167]
	global_load_lds_dwordx4 v[154:155], off
	s_waitcnt lgkmcnt(8)
	s_barrier
	s_waitcnt lgkmcnt(0)
	v_mfma_f32_16x16x32_bf16 v[126:129], v[130:133], v[146:149], v[126:129]
	v_mfma_f32_16x16x32_bf16 v[70:73], v[138:141], v[146:149], v[70:73]
	v_mfma_f32_16x16x32_bf16 v[122:125], v[130:133], v[168:171], v[122:125]
	v_mfma_f32_16x16x32_bf16 v[74:77], v[138:141], v[168:171], v[74:77]
	v_mfma_f32_16x16x32_bf16 v[114:117], v[130:133], v[176:179], v[114:117]
	v_mfma_f32_16x16x32_bf16 v[66:69], v[138:141], v[176:179], v[66:69]
	v_mfma_f32_16x16x32_bf16 v[110:113], v[130:133], v[184:187], v[110:113]
	v_mfma_f32_16x16x32_bf16 v[78:81], v[138:141], v[184:187], v[78:81]
	v_mfma_f32_16x16x32_bf16 v[126:129], v[134:137], v[150:153], v[126:129]
	v_mfma_f32_16x16x32_bf16 v[70:73], v[142:145], v[150:153], v[70:73]
	v_mfma_f32_16x16x32_bf16 v[122:125], v[134:137], v[172:175], v[122:125]
	v_mfma_f32_16x16x32_bf16 v[74:77], v[142:145], v[172:175], v[74:77]
	v_mfma_f32_16x16x32_bf16 v[114:117], v[134:137], v[180:183], v[114:117]
	v_mfma_f32_16x16x32_bf16 v[66:69], v[142:145], v[180:183], v[66:69]
	v_mfma_f32_16x16x32_bf16 v[110:113], v[134:137], v[190:193], v[110:113]
	v_mfma_f32_16x16x32_bf16 v[78:81], v[142:145], v[190:193], v[78:81]
	s_barrier
	s_add_i32 m0, s39, 0x10000
	ds_read_b128 v[194:197], v189 offset:16384
	ds_read_b128 v[198:201], v189 offset:17408
	ds_read_b128 v[202:205], v189 offset:18432
	global_load_lds_dwordx4 v160, s[90:91]
	s_add_i32 m0, s39, 0x12000
	ds_read_b128 v[206:209], v189 offset:19456
	global_load_lds_dwordx4 v156, s[90:91]
	s_barrier
	s_waitcnt lgkmcnt(0)
	v_mfma_f32_16x16x32_bf16 v[118:121], v[194:197], v[146:149], v[118:121]
	v_mfma_f32_16x16x32_bf16 v[94:97], v[202:205], v[146:149], v[94:97]
	v_mfma_f32_16x16x32_bf16 v[106:109], v[194:197], v[168:171], v[106:109]
	v_mfma_f32_16x16x32_bf16 v[90:93], v[202:205], v[168:171], v[90:93]
	v_mfma_f32_16x16x32_bf16 v[102:105], v[194:197], v[176:179], v[102:105]
	v_mfma_f32_16x16x32_bf16 v[82:85], v[202:205], v[176:179], v[82:85]
	v_mfma_f32_16x16x32_bf16 v[98:101], v[194:197], v[184:187], v[98:101]
	v_mfma_f32_16x16x32_bf16 v[86:89], v[202:205], v[184:187], v[86:89]
	v_mfma_f32_16x16x32_bf16 v[118:121], v[198:201], v[150:153], v[118:121]
	v_mfma_f32_16x16x32_bf16 v[94:97], v[206:209], v[150:153], v[94:97]
	v_mfma_f32_16x16x32_bf16 v[106:109], v[198:201], v[172:175], v[106:109]
	v_mfma_f32_16x16x32_bf16 v[90:93], v[206:209], v[172:175], v[90:93]
	v_mfma_f32_16x16x32_bf16 v[102:105], v[198:201], v[180:183], v[102:105]
	v_mfma_f32_16x16x32_bf16 v[82:85], v[206:209], v[180:183], v[82:85]
	v_mfma_f32_16x16x32_bf16 v[98:101], v[198:201], v[190:193], v[98:101]
	v_mfma_f32_16x16x32_bf16 v[86:89], v[206:209], v[190:193], v[86:89]
	s_mov_b32 m0, s43
	s_mov_b64 s[100:101], s[92:93]
	s_barrier
	ds_read_b128 v[146:149], v253 offset:16384
	ds_read_b128 v[150:153], v253 offset:17408
	ds_read_b128 v[168:171], v253 offset:18432
	ds_read_b128 v[172:175], v253 offset:19456
	ds_read_b128 v[176:179], v253 offset:20480
	ds_read_b128 v[180:183], v253 offset:21504
	ds_read_b128 v[184:187], v253 offset:22528
	global_load_lds_dwordx4 v162, s[100:101]
	s_mov_b32 m0, s60
	ds_read_b128 v[190:193], v253 offset:23552
	global_load_lds_dwordx4 v158, s[100:101]
	s_waitcnt vmcnt(10)
	s_barrier
	s_waitcnt lgkmcnt(0)
	v_mfma_f32_16x16x32_bf16 v[62:65], v[130:133], v[146:149], v[62:65]
	v_mfma_f32_16x16x32_bf16 v[10:13], v[138:141], v[146:149], v[10:13]
	v_mfma_f32_16x16x32_bf16 v[58:61], v[130:133], v[168:171], v[58:61]
	v_mfma_f32_16x16x32_bf16 v[14:17], v[138:141], v[168:171], v[14:17]
	v_mfma_f32_16x16x32_bf16 v[54:57], v[130:133], v[176:179], v[54:57]
	v_mfma_f32_16x16x32_bf16 v[6:9], v[138:141], v[176:179], v[6:9]
	v_mfma_f32_16x16x32_bf16 v[42:45], v[130:133], v[184:187], v[42:45]
	v_mfma_f32_16x16x32_bf16 v[2:5], v[138:141], v[184:187], v[2:5]
	v_mfma_f32_16x16x32_bf16 v[62:65], v[134:137], v[150:153], v[62:65]
	v_mfma_f32_16x16x32_bf16 v[10:13], v[142:145], v[150:153], v[10:13]
	v_mfma_f32_16x16x32_bf16 v[58:61], v[134:137], v[172:175], v[58:61]
	v_mfma_f32_16x16x32_bf16 v[14:17], v[142:145], v[172:175], v[14:17]
	v_mfma_f32_16x16x32_bf16 v[54:57], v[134:137], v[180:183], v[54:57]
	v_mfma_f32_16x16x32_bf16 v[6:9], v[142:145], v[180:183], v[6:9]
	v_mfma_f32_16x16x32_bf16 v[42:45], v[134:137], v[190:193], v[42:45]
	v_mfma_f32_16x16x32_bf16 v[2:5], v[142:145], v[190:193], v[2:5]
	s_barrier
	s_add_u32 s6, s90, 0x40000
	s_addc_u32 s7, s91, 0
	s_add_i32 m0, s39, 0x14000
	s_nop 0
	global_load_lds_dwordx4 v160, s[6:7]
	s_add_i32 m0, s39, 0x16000
	s_nop 0
	global_load_lds_dwordx4 v156, s[6:7]
	ds_read_b128 v[130:133], v189 offset:32768
	ds_read_b128 v[134:137], v189 offset:33792
	ds_read_b128 v[138:141], v189 offset:34816
	ds_read_b128 v[142:145], v189 offset:35840
	s_waitcnt vmcnt(6)
	s_barrier
	v_mfma_f32_16x16x32_bf16 v[50:53], v[194:197], v[146:149], v[50:53]
	v_mfma_f32_16x16x32_bf16 v[26:29], v[202:205], v[146:149], v[26:29]
	v_mfma_f32_16x16x32_bf16 v[46:49], v[194:197], v[168:171], v[46:49]
	v_mfma_f32_16x16x32_bf16 v[30:33], v[202:205], v[168:171], v[30:33]
	v_mfma_f32_16x16x32_bf16 v[38:41], v[194:197], v[176:179], v[38:41]
	v_mfma_f32_16x16x32_bf16 v[22:25], v[202:205], v[176:179], v[22:25]
	v_mfma_f32_16x16x32_bf16 v[34:37], v[194:197], v[184:187], v[34:37]
	v_mfma_f32_16x16x32_bf16 v[18:21], v[202:205], v[184:187], v[18:21]
	v_mfma_f32_16x16x32_bf16 v[50:53], v[198:201], v[150:153], v[50:53]
	v_mfma_f32_16x16x32_bf16 v[26:29], v[206:209], v[150:153], v[26:29]
	v_mfma_f32_16x16x32_bf16 v[46:49], v[198:201], v[172:175], v[46:49]
	v_mfma_f32_16x16x32_bf16 v[30:33], v[206:209], v[172:175], v[30:33]
	v_mfma_f32_16x16x32_bf16 v[38:41], v[198:201], v[180:183], v[38:41]
	v_mfma_f32_16x16x32_bf16 v[22:25], v[206:209], v[180:183], v[22:25]
	v_mfma_f32_16x16x32_bf16 v[34:37], v[198:201], v[190:193], v[34:37]
	v_mfma_f32_16x16x32_bf16 v[18:21], v[206:209], v[190:193], v[18:21]
	s_barrier
	s_add_u32 s6, s92, 0x40000
	s_addc_u32 s7, s93, 0
	s_mov_b32 m0, s61
	ds_read_b128 v[146:149], v253 offset:32768
	ds_read_b128 v[150:153], v253 offset:33792
	ds_read_b128 v[168:171], v253 offset:34816
	ds_read_b128 v[172:175], v253 offset:35840
	ds_read_b128 v[176:179], v253 offset:36864
	ds_read_b128 v[180:183], v253 offset:37888
	ds_read_b128 v[184:187], v253 offset:38912
	global_load_lds_dwordx4 v162, s[6:7]
	s_mov_b32 m0, s72
	ds_read_b128 v[190:193], v253 offset:39936
	global_load_lds_dwordx4 v158, s[6:7]
	s_waitcnt lgkmcnt(8)
	s_barrier
	s_waitcnt lgkmcnt(0)
	v_mfma_f32_16x16x32_bf16 v[126:129], v[130:133], v[146:149], v[126:129]
	v_mfma_f32_16x16x32_bf16 v[70:73], v[138:141], v[146:149], v[70:73]
	v_mfma_f32_16x16x32_bf16 v[122:125], v[130:133], v[168:171], v[122:125]
	v_mfma_f32_16x16x32_bf16 v[74:77], v[138:141], v[168:171], v[74:77]
	v_mfma_f32_16x16x32_bf16 v[114:117], v[130:133], v[176:179], v[114:117]
	v_mfma_f32_16x16x32_bf16 v[66:69], v[138:141], v[176:179], v[66:69]
	v_mfma_f32_16x16x32_bf16 v[110:113], v[130:133], v[184:187], v[110:113]
	v_mfma_f32_16x16x32_bf16 v[78:81], v[138:141], v[184:187], v[78:81]
	v_mfma_f32_16x16x32_bf16 v[126:129], v[134:137], v[150:153], v[126:129]
	v_mfma_f32_16x16x32_bf16 v[70:73], v[142:145], v[150:153], v[70:73]
	v_mfma_f32_16x16x32_bf16 v[122:125], v[134:137], v[172:175], v[122:125]
	v_mfma_f32_16x16x32_bf16 v[74:77], v[142:145], v[172:175], v[74:77]
	v_mfma_f32_16x16x32_bf16 v[114:117], v[134:137], v[180:183], v[114:117]
	v_mfma_f32_16x16x32_bf16 v[66:69], v[142:145], v[180:183], v[66:69]
	v_mfma_f32_16x16x32_bf16 v[110:113], v[134:137], v[190:193], v[110:113]
	v_mfma_f32_16x16x32_bf16 v[78:81], v[142:145], v[190:193], v[78:81]
	s_barrier
	s_add_i32 m0, s39, 0x18000
	ds_read_b128 v[194:197], v189 offset:49152
	ds_read_b128 v[198:201], v189 offset:50176
	ds_read_b128 v[202:205], v189 offset:51200
	ds_read_b128 v[206:209], v189 offset:52224
	s_add_u32 s98, s90, s40
	s_addc_u32 s99, s91, s41
	global_load_lds_dwordx4 v160, s[98:99]
	s_add_i32 m0, s39, 0x1a000
	s_nop 0
	global_load_lds_dwordx4 v156, s[98:99]
	s_barrier
	s_waitcnt lgkmcnt(0)
	v_mfma_f32_16x16x32_bf16 v[118:121], v[194:197], v[146:149], v[118:121]
	v_mfma_f32_16x16x32_bf16 v[94:97], v[202:205], v[146:149], v[94:97]
	v_mfma_f32_16x16x32_bf16 v[106:109], v[194:197], v[168:171], v[106:109]
	v_mfma_f32_16x16x32_bf16 v[90:93], v[202:205], v[168:171], v[90:93]
	v_mfma_f32_16x16x32_bf16 v[102:105], v[194:197], v[176:179], v[102:105]
	v_mfma_f32_16x16x32_bf16 v[82:85], v[202:205], v[176:179], v[82:85]
	v_mfma_f32_16x16x32_bf16 v[98:101], v[194:197], v[184:187], v[98:101]
	v_mfma_f32_16x16x32_bf16 v[86:89], v[202:205], v[184:187], v[86:89]
	v_mfma_f32_16x16x32_bf16 v[118:121], v[198:201], v[150:153], v[118:121]
	v_mfma_f32_16x16x32_bf16 v[94:97], v[206:209], v[150:153], v[94:97]
	v_mfma_f32_16x16x32_bf16 v[106:109], v[198:201], v[172:175], v[106:109]
	v_mfma_f32_16x16x32_bf16 v[90:93], v[206:209], v[172:175], v[90:93]
	v_mfma_f32_16x16x32_bf16 v[102:105], v[198:201], v[180:183], v[102:105]
	v_mfma_f32_16x16x32_bf16 v[82:85], v[206:209], v[180:183], v[82:85]
	v_mfma_f32_16x16x32_bf16 v[98:101], v[198:201], v[190:193], v[98:101]
	v_mfma_f32_16x16x32_bf16 v[86:89], v[206:209], v[190:193], v[86:89]
	s_mov_b32 m0, s95
	s_barrier
	ds_read_b128 v[146:149], v253 offset:49152
	ds_read_b128 v[150:153], v253 offset:50176
	ds_read_b128 v[168:171], v253 offset:51200
	ds_read_b128 v[172:175], v253 offset:52224
	ds_read_b128 v[176:179], v253 offset:53248
	ds_read_b128 v[180:183], v253 offset:54272
	ds_read_b128 v[184:187], v253 offset:55296
	ds_read_b128 v[190:193], v253 offset:56320
	s_add_u32 s98, s100, s40
	s_addc_u32 s99, s101, s41
	global_load_lds_dwordx4 v162, s[98:99]
	s_mov_b32 m0, s96
	s_nop 0
	global_load_lds_dwordx4 v158, s[98:99]
	s_waitcnt vmcnt(10)
	s_barrier
	s_waitcnt lgkmcnt(0)
	v_mfma_f32_16x16x32_bf16 v[62:65], v[130:133], v[146:149], v[62:65]
	v_mfma_f32_16x16x32_bf16 v[10:13], v[138:141], v[146:149], v[10:13]
	v_mfma_f32_16x16x32_bf16 v[58:61], v[130:133], v[168:171], v[58:61]
	v_mfma_f32_16x16x32_bf16 v[14:17], v[138:141], v[168:171], v[14:17]
	v_mfma_f32_16x16x32_bf16 v[54:57], v[130:133], v[176:179], v[54:57]
	v_mfma_f32_16x16x32_bf16 v[6:9], v[138:141], v[176:179], v[6:9]
	v_mfma_f32_16x16x32_bf16 v[42:45], v[130:133], v[184:187], v[42:45]
	v_mfma_f32_16x16x32_bf16 v[2:5], v[138:141], v[184:187], v[2:5]
	v_mfma_f32_16x16x32_bf16 v[62:65], v[134:137], v[150:153], v[62:65]
	v_mfma_f32_16x16x32_bf16 v[10:13], v[142:145], v[150:153], v[10:13]
	v_mfma_f32_16x16x32_bf16 v[58:61], v[134:137], v[172:175], v[58:61]
	v_mfma_f32_16x16x32_bf16 v[14:17], v[142:145], v[172:175], v[14:17]
	v_mfma_f32_16x16x32_bf16 v[54:57], v[134:137], v[180:183], v[54:57]
	v_mfma_f32_16x16x32_bf16 v[6:9], v[142:145], v[180:183], v[6:9]
	v_mfma_f32_16x16x32_bf16 v[42:45], v[134:137], v[190:193], v[42:45]
	v_mfma_f32_16x16x32_bf16 v[2:5], v[142:145], v[190:193], v[2:5]
	s_barrier
	s_add_u32 s6, s90, 0x40080
	s_addc_u32 s7, s91, 0
	s_add_i32 m0, s39, 0x1c000
	s_nop 0
	global_load_lds_dwordx4 v160, s[6:7]
	s_add_i32 m0, s39, 0x1e000
	s_nop 0
	global_load_lds_dwordx4 v156, s[6:7]
	ds_read_b128 v[130:133], v189
	ds_read_b128 v[134:137], v189 offset:1024
	ds_read_b128 v[138:141], v189 offset:2048
	ds_read_b128 v[142:145], v189 offset:3072
	s_waitcnt vmcnt(6)
	s_barrier
	v_mfma_f32_16x16x32_bf16 v[50:53], v[194:197], v[146:149], v[50:53]
	v_mfma_f32_16x16x32_bf16 v[26:29], v[202:205], v[146:149], v[26:29]
	v_mfma_f32_16x16x32_bf16 v[46:49], v[194:197], v[168:171], v[46:49]
	v_mfma_f32_16x16x32_bf16 v[30:33], v[202:205], v[168:171], v[30:33]
	v_mfma_f32_16x16x32_bf16 v[38:41], v[194:197], v[176:179], v[38:41]
	v_mfma_f32_16x16x32_bf16 v[22:25], v[202:205], v[176:179], v[22:25]
	v_mfma_f32_16x16x32_bf16 v[34:37], v[194:197], v[184:187], v[34:37]
	v_mfma_f32_16x16x32_bf16 v[18:21], v[202:205], v[184:187], v[18:21]
	v_mfma_f32_16x16x32_bf16 v[50:53], v[198:201], v[150:153], v[50:53]
	v_mfma_f32_16x16x32_bf16 v[26:29], v[206:209], v[150:153], v[26:29]
	v_mfma_f32_16x16x32_bf16 v[46:49], v[198:201], v[172:175], v[46:49]
	v_mfma_f32_16x16x32_bf16 v[30:33], v[206:209], v[172:175], v[30:33]
	v_mfma_f32_16x16x32_bf16 v[38:41], v[198:201], v[180:183], v[38:41]
	v_mfma_f32_16x16x32_bf16 v[22:25], v[206:209], v[180:183], v[22:25]
	v_mfma_f32_16x16x32_bf16 v[34:37], v[198:201], v[190:193], v[34:37]
	v_mfma_f32_16x16x32_bf16 v[18:21], v[206:209], v[190:193], v[18:21]
	s_add_i32 s45, s45, 2
	s_add_u32 s28, s28, 0x100
	s_addc_u32 s29, s29, 0
	s_mov_b64 s[6:7], s[88:89]
	s_add_u32 s88, s6, 0x100
	s_addc_u32 s89, s7, 0
	s_cmp_eq_u32 s45, 12
	s_cselect_b32 s93, s17, s89
	s_cselect_b32 s92, s22, s88
	s_cselect_b32 s91, s15, s29
	s_cselect_b32 s90, s23, s28
	s_cmp_gt_u32 s45, 13
	s_cbranch_scc0 .LBB0_919
	s_barrier
	s_waitcnt lgkmcnt(0)
	v_mov_b32_e32 v131, v252
	s_lshl_b32 s88, s5, 7
	v_bfe_u32 v130, v131, 4, 2
	v_and_b32_e32 v134, 15, v131
	v_lshlrev_b32_e32 v0, 4, v130
	s_ashr_i32 s89, s88, 31
	s_lshl_b32 s15, s4, 8
	v_or3_b32 v135, v0, s97, v134
	s_lshl_b64 s[4:5], s[88:89], 2
	v_lshrrev_b32_e32 v140, 1, v135
	s_add_u32 s4, s73, s4
	s_addc_u32 s5, s74, s5
	v_lshlrev_b32_e32 v0, 2, v140
	v_and_b32_e32 v144, 1, v131
	v_lshl_add_u64 v[132:133], s[4:5], 0, v[0:1]
	v_cmp_eq_u32_e32 vcc, 1, v144
	v_mov_b32_e32 v0, 0xb00
	s_movk_i32 s4, 0x5000
	v_cndmask_b32_e32 v141, 0, v0, vcc
	v_lshlrev_b32_e32 v0, 2, v141
	v_lshl_add_u64 v[132:133], v[132:133], 0, v[0:1]
	v_add_co_u32_e32 v138, vcc, s4, v132
	s_mov_b32 s4, 0xb000
	s_nop 0
	v_addc_co_u32_e32 v139, vcc, 0, v133, vcc
	global_load_dword v136, v[132:133], off
	global_load_dword v137, v[138:139], off offset:2048
	v_add_co_u32_e32 v132, vcc, s4, v132
	v_add_u32_e32 v0, s88, v141
	s_nop 0
	v_addc_co_u32_e32 v133, vcc, 0, v133, vcc
	global_load_dword v138, v[132:133], off
	v_or_b32_e32 v132, v140, v0
	v_ashrrev_i32_e32 v133, 31, v132
	v_lshl_add_u64 v[132:133], v[132:133], 2, s[12:13]
	global_load_dword v139, v[132:133], off
	v_lshl_add_u32 v152, v135, 4, s78
	v_and_b32_e32 v135, 63, v131
	v_cmp_eq_u32_e32 vcc, 0, v144
	v_or_b32_e32 v0, s97, v135
	v_lshrrev_b32_e32 v0, 1, v0
	v_and_or_b32 v131, v0, 63, s55
	v_add_u32_e32 v132, s15, v131
	v_ashrrev_i32_e32 v133, 31, v132
	v_lshlrev_b64 v[132:133], 6, v[132:133]
	v_lshl_add_u64 v[132:133], s[10:11], 0, v[132:133]
	v_lshlrev_b32_e32 v0, 5, v144
	v_lshl_add_u64 v[132:133], v[132:133], 0, v[0:1]
	global_load_dwordx4 v[148:151], v[132:133], off offset:16
	global_load_dwordx4 v[140:143], v[132:133], off
	s_waitcnt vmcnt(2)
	ds_write_b128 v152, v[136:139]
	s_waitcnt vmcnt(0)
	v_add_f32_e32 v133, v150, v151
	v_add_f32_e32 v0, v140, v141
	v_add_f32_e32 v132, v142, v143
	v_add_f32_e32 v0, v0, v132
	v_add_f32_e32 v132, v148, v149
	v_add_f32_e32 v132, v132, v133
	v_add_f32_e32 v0, v0, v132
	v_lshlrev_b32_e32 v132, 2, v135
	v_xor_b32_e32 v132, 4, v132
	ds_bpermute_b32 v132, v132, v0
	s_and_saveexec_b64 s[4:5], vcc
	s_cbranch_execz .LBB0_922
	s_waitcnt lgkmcnt(0)
	v_add_f32_e32 v0, v0, v132
	v_mov_b32_e32 v132, 0x358637bd
	v_fmamk_f32 v0, v0, 0x3a800000, v132
	s_mov_b32 s6, 0x800000
	v_mul_f32_e32 v132, 0x4b800000, v0
	v_cmp_gt_f32_e32 vcc, s6, v0
	v_lshl_add_u32 v131, v131, 2, 0
	v_add_u32_e32 v131, 0x20000, v131
	v_cndmask_b32_e32 v0, v0, v132, vcc
	v_rsq_f32_e32 v0, v0
	s_nop 0
	v_mul_f32_e32 v132, 0x45800000, v0
	v_cndmask_b32_e32 v0, v0, v132, vcc
	ds_write_b32 v131, v0

.LBB0_1090:
	s_barrier
	v_lshl_add_u64 v[178:179], s[16:17], 0, v[196:197]
	s_add_i32 m0, s39, 0xc000
	ds_read_b128 v[146:149], v213
	ds_read_b128 v[150:153], v213 offset:1024
	ds_read_b128 v[154:157], v213 offset:2048
	ds_read_b128 v[158:161], v213 offset:3072
	ds_read_b128 v[162:165], v213 offset:4096
	ds_read_b128 v[166:169], v213 offset:5120
	ds_read_b128 v[170:173], v213 offset:6144
	ds_read_b128 v[174:177], v213 offset:7168
	global_load_lds_dwordx4 v[178:179], off
	s_add_i32 m0, s39, 0xe000
	v_lshl_add_u64 v[178:179], s[16:17], 0, v[198:199]
	global_load_lds_dwordx4 v[178:179], off
	s_waitcnt lgkmcnt(8)
	s_barrier
	s_waitcnt lgkmcnt(0)
	v_mfma_f32_16x16x32_bf16 v[126:129], v[130:133], v[146:149], v[126:129]
	v_mfma_f32_16x16x32_bf16 v[122:125], v[138:141], v[146:149], v[122:125]
	v_mfma_f32_16x16x32_bf16 v[110:113], v[130:133], v[154:157], v[110:113]
	v_mfma_f32_16x16x32_bf16 v[106:109], v[138:141], v[154:157], v[106:109]
	v_mfma_f32_16x16x32_bf16 v[94:97], v[130:133], v[162:165], v[94:97]
	v_mfma_f32_16x16x32_bf16 v[90:93], v[138:141], v[162:165], v[90:93]
	v_mfma_f32_16x16x32_bf16 v[78:81], v[130:133], v[170:173], v[78:81]
	v_mfma_f32_16x16x32_bf16 v[74:77], v[138:141], v[170:173], v[74:77]
	v_mfma_f32_16x16x32_bf16 v[126:129], v[134:137], v[150:153], v[126:129]
	v_mfma_f32_16x16x32_bf16 v[122:125], v[142:145], v[150:153], v[122:125]
	v_mfma_f32_16x16x32_bf16 v[110:113], v[134:137], v[158:161], v[110:113]
	v_mfma_f32_16x16x32_bf16 v[106:109], v[142:145], v[158:161], v[106:109]
	v_mfma_f32_16x16x32_bf16 v[94:97], v[134:137], v[166:169], v[94:97]
	v_mfma_f32_16x16x32_bf16 v[90:93], v[142:145], v[166:169], v[90:93]
	v_mfma_f32_16x16x32_bf16 v[78:81], v[134:137], v[174:177], v[78:81]
	v_mfma_f32_16x16x32_bf16 v[74:77], v[142:145], v[174:177], v[74:77]
	s_barrier
	ds_read_b128 v[178:181], v189 offset:16384
	ds_read_b128 v[182:185], v189 offset:17408
	ds_read_b128 v[200:203], v189 offset:18432
	ds_read_b128 v[204:207], v189 offset:19456
	s_add_i32 m0, s38, 0x10000
	s_nop 0
	global_load_lds_dwordx4 v0, s[86:87]
	s_add_i32 m0, s38, 0x12000
	s_nop 0
	global_load_lds_dwordx4 v194, s[86:87]
	s_barrier
	s_waitcnt lgkmcnt(0)
	v_mfma_f32_16x16x32_bf16 v[118:121], v[178:181], v[146:149], v[118:121]
	v_mfma_f32_16x16x32_bf16 v[114:117], v[200:203], v[146:149], v[114:117]
	v_mfma_f32_16x16x32_bf16 v[102:105], v[178:181], v[154:157], v[102:105]
	v_mfma_f32_16x16x32_bf16 v[98:101], v[200:203], v[154:157], v[98:101]
	v_mfma_f32_16x16x32_bf16 v[86:89], v[178:181], v[162:165], v[86:89]
	v_mfma_f32_16x16x32_bf16 v[82:85], v[200:203], v[162:165], v[82:85]
	v_mfma_f32_16x16x32_bf16 v[70:73], v[178:181], v[170:173], v[70:73]
	v_mfma_f32_16x16x32_bf16 v[66:69], v[200:203], v[170:173], v[66:69]
	v_mfma_f32_16x16x32_bf16 v[118:121], v[182:185], v[150:153], v[118:121]
	v_mfma_f32_16x16x32_bf16 v[114:117], v[204:207], v[150:153], v[114:117]
	v_mfma_f32_16x16x32_bf16 v[102:105], v[182:185], v[158:161], v[102:105]
	v_mfma_f32_16x16x32_bf16 v[98:101], v[204:207], v[158:161], v[98:101]
	v_mfma_f32_16x16x32_bf16 v[86:89], v[182:185], v[166:169], v[86:89]
	v_mfma_f32_16x16x32_bf16 v[82:85], v[204:207], v[166:169], v[82:85]
	v_mfma_f32_16x16x32_bf16 v[70:73], v[182:185], v[174:177], v[70:73]
	v_mfma_f32_16x16x32_bf16 v[66:69], v[204:207], v[174:177], v[66:69]
	s_mov_b32 m0, s39
	s_mov_b64 s[100:101], s[88:89]
	s_barrier
	ds_read_b128 v[146:149], v213 offset:16384
	ds_read_b128 v[150:153], v213 offset:17408
	ds_read_b128 v[154:157], v213 offset:18432
	ds_read_b128 v[158:161], v213 offset:19456
	ds_read_b128 v[162:165], v213 offset:20480
	ds_read_b128 v[166:169], v213 offset:21504
	ds_read_b128 v[170:173], v213 offset:22528
	global_load_lds_dwordx4 v190, s[100:101]
	s_mov_b32 m0, s42
	ds_read_b128 v[174:177], v213 offset:23552
	global_load_lds_dwordx4 v192, s[100:101]
	s_waitcnt vmcnt(10)
	s_barrier
	s_waitcnt lgkmcnt(0)
	v_mfma_f32_16x16x32_bf16 v[62:65], v[130:133], v[146:149], v[62:65]
	v_mfma_f32_16x16x32_bf16 v[58:61], v[138:141], v[146:149], v[58:61]
	v_mfma_f32_16x16x32_bf16 v[46:49], v[130:133], v[154:157], v[46:49]
	v_mfma_f32_16x16x32_bf16 v[42:45], v[138:141], v[154:157], v[42:45]
	v_mfma_f32_16x16x32_bf16 v[30:33], v[130:133], v[162:165], v[30:33]
	v_mfma_f32_16x16x32_bf16 v[26:29], v[138:141], v[162:165], v[26:29]
	v_mfma_f32_16x16x32_bf16 v[14:17], v[130:133], v[170:173], v[14:17]
	v_mfma_f32_16x16x32_bf16 v[10:13], v[138:141], v[170:173], v[10:13]
	v_mfma_f32_16x16x32_bf16 v[62:65], v[134:137], v[150:153], v[62:65]
	v_mfma_f32_16x16x32_bf16 v[58:61], v[142:145], v[150:153], v[58:61]
	v_mfma_f32_16x16x32_bf16 v[46:49], v[134:137], v[158:161], v[46:49]
	v_mfma_f32_16x16x32_bf16 v[42:45], v[142:145], v[158:161], v[42:45]
	v_mfma_f32_16x16x32_bf16 v[30:33], v[134:137], v[166:169], v[30:33]
	v_mfma_f32_16x16x32_bf16 v[26:29], v[142:145], v[166:169], v[26:29]
	v_mfma_f32_16x16x32_bf16 v[14:17], v[134:137], v[174:177], v[14:17]
	v_mfma_f32_16x16x32_bf16 v[10:13], v[142:145], v[174:177], v[10:13]
	s_barrier
	s_add_u32 s16, s86, 0xb0000
	s_addc_u32 s17, s87, 0
	s_add_i32 m0, s38, 0x14000
	s_nop 0
	global_load_lds_dwordx4 v0, s[16:17]
	s_add_i32 m0, s38, 0x16000
	s_nop 0
	global_load_lds_dwordx4 v194, s[16:17]
	s_add_i32 s90, 0, 0x18000
	v_add_u32_e32 v142, s90, v212
	ds_read_b128 v[130:133], v142
	ds_read_b128 v[134:137], v142 offset:1024
	ds_read_b128 v[138:141], v142 offset:2048
	ds_read_b128 v[142:145], v142 offset:3072
	s_waitcnt vmcnt(6)
	s_barrier
	v_mfma_f32_16x16x32_bf16 v[54:57], v[178:181], v[146:149], v[54:57]
	v_mfma_f32_16x16x32_bf16 v[50:53], v[200:203], v[146:149], v[50:53]
	v_mfma_f32_16x16x32_bf16 v[38:41], v[178:181], v[154:157], v[38:41]
	v_mfma_f32_16x16x32_bf16 v[34:37], v[200:203], v[154:157], v[34:37]
	v_mfma_f32_16x16x32_bf16 v[22:25], v[178:181], v[162:165], v[22:25]
	v_mfma_f32_16x16x32_bf16 v[18:21], v[200:203], v[162:165], v[18:21]
	v_mfma_f32_16x16x32_bf16 v[6:9], v[178:181], v[170:173], v[6:9]
	v_mfma_f32_16x16x32_bf16 v[2:5], v[200:203], v[170:173], v[2:5]
	v_mfma_f32_16x16x32_bf16 v[54:57], v[182:185], v[150:153], v[54:57]
	v_mfma_f32_16x16x32_bf16 v[50:53], v[204:207], v[150:153], v[50:53]
	v_mfma_f32_16x16x32_bf16 v[38:41], v[182:185], v[158:161], v[38:41]
	v_mfma_f32_16x16x32_bf16 v[34:37], v[204:207], v[158:161], v[34:37]
	v_mfma_f32_16x16x32_bf16 v[22:25], v[182:185], v[166:169], v[22:25]
	v_mfma_f32_16x16x32_bf16 v[18:21], v[204:207], v[166:169], v[18:21]
	v_mfma_f32_16x16x32_bf16 v[6:9], v[182:185], v[174:177], v[6:9]
	v_mfma_f32_16x16x32_bf16 v[2:5], v[204:207], v[174:177], v[2:5]
	s_barrier
	s_add_u32 s16, s88, 0xb0000
	s_addc_u32 s17, s89, 0
	s_mov_b32 m0, s43
	ds_read_b128 v[146:149], v213 offset:32768
	ds_read_b128 v[150:153], v213 offset:33792
	ds_read_b128 v[154:157], v213 offset:34816
	ds_read_b128 v[158:161], v213 offset:35840
	ds_read_b128 v[162:165], v213 offset:36864
	ds_read_b128 v[166:169], v213 offset:37888
	ds_read_b128 v[170:173], v213 offset:38912
	global_load_lds_dwordx4 v190, s[16:17]
	s_mov_b32 m0, s44
	ds_read_b128 v[174:177], v213 offset:39936
	global_load_lds_dwordx4 v192, s[16:17]
	s_waitcnt lgkmcnt(8)
	s_barrier
	s_waitcnt lgkmcnt(0)
	v_mfma_f32_16x16x32_bf16 v[126:129], v[130:133], v[146:149], v[126:129]
	v_mfma_f32_16x16x32_bf16 v[122:125], v[138:141], v[146:149], v[122:125]
	v_mfma_f32_16x16x32_bf16 v[110:113], v[130:133], v[154:157], v[110:113]
	v_mfma_f32_16x16x32_bf16 v[106:109], v[138:141], v[154:157], v[106:109]
	v_mfma_f32_16x16x32_bf16 v[94:97], v[130:133], v[162:165], v[94:97]
	v_mfma_f32_16x16x32_bf16 v[90:93], v[138:141], v[162:165], v[90:93]
	v_mfma_f32_16x16x32_bf16 v[78:81], v[130:133], v[170:173], v[78:81]
	v_mfma_f32_16x16x32_bf16 v[74:77], v[138:141], v[170:173], v[74:77]
	v_mfma_f32_16x16x32_bf16 v[126:129], v[134:137], v[150:153], v[126:129]
	v_mfma_f32_16x16x32_bf16 v[122:125], v[142:145], v[150:153], v[122:125]
	v_mfma_f32_16x16x32_bf16 v[110:113], v[134:137], v[158:161], v[110:113]
	v_mfma_f32_16x16x32_bf16 v[106:109], v[142:145], v[158:161], v[106:109]
	v_mfma_f32_16x16x32_bf16 v[94:97], v[134:137], v[166:169], v[94:97]
	v_mfma_f32_16x16x32_bf16 v[90:93], v[142:145], v[166:169], v[90:93]
	v_mfma_f32_16x16x32_bf16 v[78:81], v[134:137], v[174:177], v[78:81]
	v_mfma_f32_16x16x32_bf16 v[74:77], v[142:145], v[174:177], v[74:77]
	s_barrier
	s_add_i32 s88, 0, 0x1c000
	v_add_u32_e32 v204, s88, v212
	s_add_i32 m0, s38, 0x18000
	ds_read_b128 v[178:181], v204
	ds_read_b128 v[182:185], v204 offset:1024
	ds_read_b128 v[200:203], v204 offset:2048
	ds_read_b128 v[204:207], v204 offset:3072
	s_add_u32 s98, s86, s40
	s_addc_u32 s99, s87, s41
	global_load_lds_dwordx4 v0, s[98:99]
	s_add_i32 m0, s38, 0x1a000
	s_nop 0
	global_load_lds_dwordx4 v194, s[98:99]
	s_barrier
	s_waitcnt lgkmcnt(0)
	v_mfma_f32_16x16x32_bf16 v[118:121], v[178:181], v[146:149], v[118:121]
	v_mfma_f32_16x16x32_bf16 v[114:117], v[200:203], v[146:149], v[114:117]
	v_mfma_f32_16x16x32_bf16 v[102:105], v[178:181], v[154:157], v[102:105]
	v_mfma_f32_16x16x32_bf16 v[98:101], v[200:203], v[154:157], v[98:101]
	v_mfma_f32_16x16x32_bf16 v[86:89], v[178:181], v[162:165], v[86:89]
	v_mfma_f32_16x16x32_bf16 v[82:85], v[200:203], v[162:165], v[82:85]
	v_mfma_f32_16x16x32_bf16 v[70:73], v[178:181], v[170:173], v[70:73]
	v_mfma_f32_16x16x32_bf16 v[66:69], v[200:203], v[170:173], v[66:69]
	v_mfma_f32_16x16x32_bf16 v[118:121], v[182:185], v[150:153], v[118:121]
	v_mfma_f32_16x16x32_bf16 v[114:117], v[204:207], v[150:153], v[114:117]
	v_mfma_f32_16x16x32_bf16 v[102:105], v[182:185], v[158:161], v[102:105]
	v_mfma_f32_16x16x32_bf16 v[98:101], v[204:207], v[158:161], v[98:101]
	v_mfma_f32_16x16x32_bf16 v[86:89], v[182:185], v[166:169], v[86:89]
	v_mfma_f32_16x16x32_bf16 v[82:85], v[204:207], v[166:169], v[82:85]
	v_mfma_f32_16x16x32_bf16 v[70:73], v[182:185], v[174:177], v[70:73]
	v_mfma_f32_16x16x32_bf16 v[66:69], v[204:207], v[174:177], v[66:69]
	s_mov_b32 m0, s60
	s_barrier
	ds_read_b128 v[146:149], v213 offset:49152
	ds_read_b128 v[150:153], v213 offset:50176
	ds_read_b128 v[154:157], v213 offset:51200
	ds_read_b128 v[158:161], v213 offset:52224
	ds_read_b128 v[162:165], v213 offset:53248
	ds_read_b128 v[166:169], v213 offset:54272
	ds_read_b128 v[170:173], v213 offset:55296
	ds_read_b128 v[174:177], v213 offset:56320
	s_add_u32 s98, s100, s40
	s_addc_u32 s99, s101, s41
	global_load_lds_dwordx4 v190, s[98:99]
	s_mov_b32 m0, s61
	s_nop 0
	global_load_lds_dwordx4 v192, s[98:99]
	s_waitcnt vmcnt(10)
	s_barrier
	s_waitcnt lgkmcnt(0)
	v_mfma_f32_16x16x32_bf16 v[62:65], v[130:133], v[146:149], v[62:65]
	v_mfma_f32_16x16x32_bf16 v[58:61], v[138:141], v[146:149], v[58:61]
	v_mfma_f32_16x16x32_bf16 v[46:49], v[130:133], v[154:157], v[46:49]
	v_mfma_f32_16x16x32_bf16 v[42:45], v[138:141], v[154:157], v[42:45]
	v_mfma_f32_16x16x32_bf16 v[30:33], v[130:133], v[162:165], v[30:33]
	v_mfma_f32_16x16x32_bf16 v[26:29], v[138:141], v[162:165], v[26:29]
	v_mfma_f32_16x16x32_bf16 v[14:17], v[130:133], v[170:173], v[14:17]
	v_mfma_f32_16x16x32_bf16 v[10:13], v[138:141], v[170:173], v[10:13]
	v_mfma_f32_16x16x32_bf16 v[62:65], v[134:137], v[150:153], v[62:65]
	v_mfma_f32_16x16x32_bf16 v[58:61], v[142:145], v[150:153], v[58:61]
	v_mfma_f32_16x16x32_bf16 v[46:49], v[134:137], v[158:161], v[46:49]
	v_mfma_f32_16x16x32_bf16 v[42:45], v[142:145], v[158:161], v[42:45]
	v_mfma_f32_16x16x32_bf16 v[30:33], v[134:137], v[166:169], v[30:33]
	v_mfma_f32_16x16x32_bf16 v[26:29], v[142:145], v[166:169], v[26:29]
	v_mfma_f32_16x16x32_bf16 v[14:17], v[134:137], v[174:177], v[14:17]
	v_mfma_f32_16x16x32_bf16 v[10:13], v[142:145], v[174:177], v[10:13]
	s_barrier
	s_add_u32 s16, s86, 0xb0080
	s_addc_u32 s17, s87, 0
	s_add_i32 m0, s38, 0x1c000
	s_nop 0
	global_load_lds_dwordx4 v0, s[16:17]
	s_add_i32 m0, s38, 0x1e000
	s_nop 0
	global_load_lds_dwordx4 v194, s[16:17]
	ds_read_b128 v[130:133], v189
	ds_read_b128 v[134:137], v189 offset:1024
	ds_read_b128 v[138:141], v189 offset:2048
	ds_read_b128 v[142:145], v189 offset:3072
	s_waitcnt vmcnt(6)
	s_barrier
	v_mfma_f32_16x16x32_bf16 v[54:57], v[178:181], v[146:149], v[54:57]
	v_mfma_f32_16x16x32_bf16 v[50:53], v[200:203], v[146:149], v[50:53]
	v_mfma_f32_16x16x32_bf16 v[38:41], v[178:181], v[154:157], v[38:41]
	v_mfma_f32_16x16x32_bf16 v[34:37], v[200:203], v[154:157], v[34:37]
	v_mfma_f32_16x16x32_bf16 v[22:25], v[178:181], v[162:165], v[22:25]
	v_mfma_f32_16x16x32_bf16 v[18:21], v[200:203], v[162:165], v[18:21]
	v_mfma_f32_16x16x32_bf16 v[6:9], v[178:181], v[170:173], v[6:9]
	v_mfma_f32_16x16x32_bf16 v[2:5], v[200:203], v[170:173], v[2:5]
	v_mfma_f32_16x16x32_bf16 v[54:57], v[182:185], v[150:153], v[54:57]
	v_mfma_f32_16x16x32_bf16 v[50:53], v[204:207], v[150:153], v[50:53]
	v_mfma_f32_16x16x32_bf16 v[38:41], v[182:185], v[158:161], v[38:41]
	v_mfma_f32_16x16x32_bf16 v[34:37], v[204:207], v[158:161], v[34:37]
	v_mfma_f32_16x16x32_bf16 v[22:25], v[182:185], v[166:169], v[22:25]
	v_mfma_f32_16x16x32_bf16 v[18:21], v[204:207], v[166:169], v[18:21]
	v_mfma_f32_16x16x32_bf16 v[6:9], v[182:185], v[174:177], v[6:9]
	v_mfma_f32_16x16x32_bf16 v[2:5], v[204:207], v[174:177], v[2:5]
	s_add_i32 s79, s79, 2
	s_add_u32 s34, s34, 0x100
	s_addc_u32 s78, s78, 0
	s_mov_b64 s[16:17], s[84:85]
	s_add_u32 s84, s16, 0x100
	s_addc_u32 s85, s17, 0
	s_cmp_eq_u32 s79, 40
	s_cselect_b32 s89, s5, s85
	s_cselect_b32 s88, s4, s84
	s_cselect_b32 s87, s7, s78
	s_cselect_b32 s86, s6, s34
	s_cmp_gt_u32 s79, 41
	s_cbranch_scc0 .LBB0_1090
	s_barrier
	s_waitcnt lgkmcnt(0)
	s_lshl_b32 s16, s23, 8
	v_mov_b32_e32 v186, v252
	s_add_i32 s16, s16, s47
	s_nop 0
	v_and_or_b32 v202, v186, 15, s16
	s_lshl_b32 s16, s22, 8
	s_or_b32 s16, s16, s55
	v_lshrrev_b32_e32 v130, 1, v186
	v_and_or_b32 v200, v130, 24, s16
	v_ashrrev_i32_e32 v201, 31, v200
	v_ashrrev_i32_e32 v203, 31, v202
	v_lshl_add_u64 v[204:205], v[200:201], 2, s[12:13]
	v_lshlrev_b64 v[130:131], 12, v[202:203]
	v_lshl_add_u64 v[130:131], v[204:205], 0, v[130:131]
	global_load_dwordx4 v[216:219], v[130:131], off offset:16
	global_load_dwordx4 v[220:223], v[130:131], off
	global_load_dwordx4 v[178:181], v[130:131], off offset:528
	global_load_dwordx4 v[182:185], v[130:131], off offset:512
	v_or_b32_e32 v210, 16, v202
	v_ashrrev_i32_e32 v211, 31, v210
	v_lshlrev_b64 v[130:131], 12, v[210:211]
	v_or_b32_e32 v208, 32, v202
	v_lshl_add_u64 v[130:131], v[204:205], 0, v[130:131]
	v_ashrrev_i32_e32 v209, 31, v208
	global_load_dwordx4 v[170:173], v[130:131], off offset:16
	global_load_dwordx4 v[174:177], v[130:131], off
	global_load_dwordx4 v[162:165], v[130:131], off offset:528
	global_load_dwordx4 v[166:169], v[130:131], off offset:512
	v_lshlrev_b64 v[130:131], 12, v[208:209]
	v_or_b32_e32 v206, 48, v202
	v_lshl_add_u64 v[130:131], v[204:205], 0, v[130:131]
	v_ashrrev_i32_e32 v207, 31, v206
	global_load_dwordx4 v[154:157], v[130:131], off offset:16
	global_load_dwordx4 v[158:161], v[130:131], off
	global_load_dwordx4 v[138:141], v[130:131], off offset:528
	global_load_dwordx4 v[142:145], v[130:131], off offset:512
	v_lshlrev_b64 v[130:131], 12, v[206:207]
	v_lshl_add_u64 v[134:135], v[204:205], 0, v[130:131]
	global_load_dwordx4 v[146:149], v[134:135], off offset:16
	global_load_dwordx4 v[150:153], v[134:135], off
	global_load_dwordx4 v[130:133], v[134:135], off offset:528
	s_nop 0
	global_load_dwordx4 v[134:137], v[134:135], off offset:512
	v_and_b32_e32 v186, 63, v186
	v_lshlrev_b32_e32 v187, 2, v186
	v_xor_b32_e32 v215, 64, v187
	v_xor_b32_e32 v214, 0x80, v187
	v_cmp_gt_u32_e32 vcc, 16, v186
	v_lshlrev_b64 v[186:187], 10, v[202:203]
	v_lshl_add_u64 v[186:187], v[186:187], 0, v[200:201]
	s_lshl_b32 s16, s22, 2
	s_ashr_i32 s17, s16, 31
	s_waitcnt vmcnt(0)
	v_pk_add_f32 v[124:125], v[124:125], v[218:219]
	v_pk_add_f32 v[128:129], v[128:129], v[222:223]
	v_pk_add_f32 v[126:127], v[126:127], v[220:221]
	v_pk_mul_f32 v[218:219], v[128:129], v[128:129]
	v_pk_mul_f32 v[220:221], v[126:127], v[126:127]
	v_pk_add_f32 v[122:123], v[122:123], v[216:217]
	v_lshl_add_u64 v[216:217], v[186:187], 2, s[14:15]
	v_add_f32_e32 v220, v220, v221
	v_add_f32_e32 v218, v218, v219
	global_store_dwordx4 v[216:217], v[126:129], off
	global_store_dwordx4 v[216:217], v[122:125], off offset:16
	v_add_f32_e32 v222, v220, v218
	v_pk_mul_f32 v[220:221], v[122:123], v[122:123]
	v_cvt_pk_bf16_f32 v126, v126, v127
	v_cvt_pk_bf16_f32 v127, v128, v129
	v_cvt_pk_bf16_f32 v128, v122, v123
	v_cvt_pk_bf16_f32 v129, v124, v125
	v_lshl_add_u64 v[122:123], v[186:187], 1, s[80:81]
	v_pk_add_f32 v[120:121], v[120:121], v[184:185]
	v_pk_add_f32 v[118:119], v[118:119], v[182:183]
	v_pk_mul_f32 v[218:219], v[124:125], v[124:125]
	global_store_dwordx4 v[122:123], v[126:129], off
	v_pk_mul_f32 v[124:125], v[120:121], v[120:121]
	v_pk_add_f32 v[116:117], v[116:117], v[180:181]
	v_pk_mul_f32 v[126:127], v[118:119], v[118:119]
	v_pk_add_f32 v[114:115], v[114:115], v[178:179]
	v_add_f32_e32 v126, v126, v127
	v_add_f32_e32 v124, v124, v125
	v_add_f32_e32 v128, v126, v124
	v_pk_mul_f32 v[124:125], v[116:117], v[116:117]
	v_pk_mul_f32 v[126:127], v[114:115], v[114:115]
	v_add_f32_e32 v220, v220, v221
	v_add_f32_e32 v218, v218, v219
	v_add_f32_e32 v126, v126, v127
	v_add_f32_e32 v124, v124, v125
	v_add_f32_e32 v218, v220, v218
	v_add_f32_e32 v124, v126, v124
	v_add_f32_e32 v218, v222, v218
	v_add_f32_e32 v124, v128, v124
	v_add_f32_e32 v124, v218, v124
	global_store_dwordx4 v[216:217], v[118:121], off offset:512
	global_store_dwordx4 v[216:217], v[114:117], off offset:528
	s_nop 0
	v_cvt_pk_bf16_f32 v118, v118, v119
	v_cvt_pk_bf16_f32 v119, v120, v121
	v_cvt_pk_bf16_f32 v120, v114, v115
	ds_bpermute_b32 v114, v215, v124
	v_cvt_pk_bf16_f32 v121, v116, v117
	global_store_dwordx4 v[122:123], v[118:121], off offset:256
	s_waitcnt lgkmcnt(0)
	v_add_f32_e32 v114, v124, v114
	ds_bpermute_b32 v115, v214, v114
	s_and_saveexec_b64 s[22:23], vcc
	s_cbranch_execz .LBB0_1093
	v_lshlrev_b64 v[116:117], 6, v[202:203]
	v_lshl_add_u64 v[116:117], s[82:83], 0, v[116:117]
	v_lshl_add_u64 v[116:117], s[16:17], 2, v[116:117]
	s_lshl_b32 s34, s45, 2
	v_lshl_add_u64 v[116:117], v[116:117], 0, s[34:35]
	s_waitcnt lgkmcnt(0)
	v_add_f32_e32 v114, v114, v115
	global_store_dword v[116:117], v114, off

.LBB0_1209:
	s_barrier
	s_waitcnt lgkmcnt(0)
	s_add_i32 m0, s39, 0xc000
	ds_read_b128 v[158:161], v171
	ds_read_b128 v[162:165], v171 offset:1024
	ds_read_b128 v[166:169], v171 offset:2048
	ds_read_b128 v[172:175], v171 offset:3072
	ds_read_b128 v[176:179], v171 offset:4096
	ds_read_b128 v[180:183], v171 offset:5120
	ds_read_b128 v[184:187], v171 offset:6144
	global_load_lds_dwordx4 v154, s[88:89]
	s_add_i32 m0, s39, 0xe000
	ds_read_b128 v[190:193], v171 offset:7168
	global_load_lds_dwordx4 v156, s[88:89]
	s_waitcnt lgkmcnt(8)
	s_barrier
	s_waitcnt lgkmcnt(0)
	v_mfma_f32_16x16x32_bf16 v[126:129], v[130:133], v[158:161], v[126:129]
	v_mfma_f32_16x16x32_bf16 v[122:125], v[138:141], v[158:161], v[122:125]
	v_mfma_f32_16x16x32_bf16 v[110:113], v[130:133], v[166:169], v[110:113]
	v_mfma_f32_16x16x32_bf16 v[106:109], v[138:141], v[166:169], v[106:109]
	v_mfma_f32_16x16x32_bf16 v[94:97], v[130:133], v[176:179], v[94:97]
	v_mfma_f32_16x16x32_bf16 v[90:93], v[138:141], v[176:179], v[90:93]
	v_mfma_f32_16x16x32_bf16 v[78:81], v[130:133], v[184:187], v[78:81]
	v_mfma_f32_16x16x32_bf16 v[74:77], v[138:141], v[184:187], v[74:77]
	v_mfma_f32_16x16x32_bf16 v[126:129], v[134:137], v[162:165], v[126:129]
	v_mfma_f32_16x16x32_bf16 v[122:125], v[142:145], v[162:165], v[122:125]
	v_mfma_f32_16x16x32_bf16 v[110:113], v[134:137], v[172:175], v[110:113]
	v_mfma_f32_16x16x32_bf16 v[106:109], v[142:145], v[172:175], v[106:109]
	v_mfma_f32_16x16x32_bf16 v[94:97], v[134:137], v[180:183], v[94:97]
	v_mfma_f32_16x16x32_bf16 v[90:93], v[142:145], v[180:183], v[90:93]
	v_mfma_f32_16x16x32_bf16 v[78:81], v[134:137], v[190:193], v[78:81]
	v_mfma_f32_16x16x32_bf16 v[74:77], v[142:145], v[190:193], v[74:77]
	s_barrier
	s_add_i32 m0, s38, 0x10000
	ds_read_b128 v[194:197], v189 offset:16384
	ds_read_b128 v[198:201], v189 offset:17408
	ds_read_b128 v[202:205], v189 offset:18432
	global_load_lds_dwordx4 v148, s[90:91]
	s_add_i32 m0, s38, 0x12000
	ds_read_b128 v[206:209], v189 offset:19456
	global_load_lds_dwordx4 v152, s[90:91]
	s_barrier
	s_waitcnt lgkmcnt(0)
	v_mfma_f32_16x16x32_bf16 v[118:121], v[194:197], v[158:161], v[118:121]
	v_mfma_f32_16x16x32_bf16 v[114:117], v[202:205], v[158:161], v[114:117]
	v_mfma_f32_16x16x32_bf16 v[102:105], v[194:197], v[166:169], v[102:105]
	v_mfma_f32_16x16x32_bf16 v[98:101], v[202:205], v[166:169], v[98:101]
	v_mfma_f32_16x16x32_bf16 v[86:89], v[194:197], v[176:179], v[86:89]
	v_mfma_f32_16x16x32_bf16 v[82:85], v[202:205], v[176:179], v[82:85]
	v_mfma_f32_16x16x32_bf16 v[70:73], v[194:197], v[184:187], v[70:73]
	v_mfma_f32_16x16x32_bf16 v[66:69], v[202:205], v[184:187], v[66:69]
	v_mfma_f32_16x16x32_bf16 v[118:121], v[198:201], v[162:165], v[118:121]
	v_mfma_f32_16x16x32_bf16 v[114:117], v[206:209], v[162:165], v[114:117]
	v_mfma_f32_16x16x32_bf16 v[102:105], v[198:201], v[172:175], v[102:105]
	v_mfma_f32_16x16x32_bf16 v[98:101], v[206:209], v[172:175], v[98:101]
	v_mfma_f32_16x16x32_bf16 v[86:89], v[198:201], v[180:183], v[86:89]
	v_mfma_f32_16x16x32_bf16 v[82:85], v[206:209], v[180:183], v[82:85]
	v_mfma_f32_16x16x32_bf16 v[70:73], v[198:201], v[190:193], v[70:73]
	v_mfma_f32_16x16x32_bf16 v[66:69], v[206:209], v[190:193], v[66:69]
	s_mov_b32 m0, s39
	s_mov_b64 s[100:101], s[92:93]
	s_barrier
	ds_read_b128 v[158:161], v171 offset:16384
	ds_read_b128 v[162:165], v171 offset:17408
	ds_read_b128 v[166:169], v171 offset:18432
	ds_read_b128 v[172:175], v171 offset:19456
	ds_read_b128 v[176:179], v171 offset:20480
	ds_read_b128 v[180:183], v171 offset:21504
	ds_read_b128 v[184:187], v171 offset:22528
	global_load_lds_dwordx4 v146, s[100:101]
	s_mov_b32 m0, s42
	ds_read_b128 v[190:193], v171 offset:23552
	global_load_lds_dwordx4 v150, s[100:101]
	s_waitcnt vmcnt(10)
	s_barrier
	s_waitcnt lgkmcnt(0)
	v_mfma_f32_16x16x32_bf16 v[62:65], v[130:133], v[158:161], v[62:65]
	v_mfma_f32_16x16x32_bf16 v[58:61], v[138:141], v[158:161], v[58:61]
	v_mfma_f32_16x16x32_bf16 v[46:49], v[130:133], v[166:169], v[46:49]
	v_mfma_f32_16x16x32_bf16 v[42:45], v[138:141], v[166:169], v[42:45]
	v_mfma_f32_16x16x32_bf16 v[30:33], v[130:133], v[176:179], v[30:33]
	v_mfma_f32_16x16x32_bf16 v[26:29], v[138:141], v[176:179], v[26:29]
	v_mfma_f32_16x16x32_bf16 v[14:17], v[130:133], v[184:187], v[14:17]
	v_mfma_f32_16x16x32_bf16 v[10:13], v[138:141], v[184:187], v[10:13]
	v_mfma_f32_16x16x32_bf16 v[62:65], v[134:137], v[162:165], v[62:65]
	v_mfma_f32_16x16x32_bf16 v[58:61], v[142:145], v[162:165], v[58:61]
	v_mfma_f32_16x16x32_bf16 v[46:49], v[134:137], v[172:175], v[46:49]
	v_mfma_f32_16x16x32_bf16 v[42:45], v[142:145], v[172:175], v[42:45]
	v_mfma_f32_16x16x32_bf16 v[30:33], v[134:137], v[180:183], v[30:33]
	v_mfma_f32_16x16x32_bf16 v[26:29], v[142:145], v[180:183], v[26:29]
	v_mfma_f32_16x16x32_bf16 v[14:17], v[134:137], v[190:193], v[14:17]
	v_mfma_f32_16x16x32_bf16 v[10:13], v[142:145], v[190:193], v[10:13]
	s_barrier
	s_add_u32 s94, s90, 0x40000
	s_addc_u32 s95, s91, 0
	s_add_i32 m0, s38, 0x14000
	s_nop 0
	global_load_lds_dwordx4 v148, s[94:95]
	s_add_i32 m0, s38, 0x16000
	s_nop 0
	global_load_lds_dwordx4 v152, s[94:95]
	ds_read_b128 v[130:133], v189 offset:32768
	ds_read_b128 v[134:137], v189 offset:33792
	ds_read_b128 v[138:141], v189 offset:34816
	ds_read_b128 v[142:145], v189 offset:35840
	s_waitcnt vmcnt(6)
	s_barrier
	v_mfma_f32_16x16x32_bf16 v[54:57], v[194:197], v[158:161], v[54:57]
	v_mfma_f32_16x16x32_bf16 v[50:53], v[202:205], v[158:161], v[50:53]
	v_mfma_f32_16x16x32_bf16 v[38:41], v[194:197], v[166:169], v[38:41]
	v_mfma_f32_16x16x32_bf16 v[34:37], v[202:205], v[166:169], v[34:37]
	v_mfma_f32_16x16x32_bf16 v[22:25], v[194:197], v[176:179], v[22:25]
	v_mfma_f32_16x16x32_bf16 v[18:21], v[202:205], v[176:179], v[18:21]
	v_mfma_f32_16x16x32_bf16 v[6:9], v[194:197], v[184:187], v[6:9]
	v_mfma_f32_16x16x32_bf16 v[2:5], v[202:205], v[184:187], v[2:5]
	v_mfma_f32_16x16x32_bf16 v[54:57], v[198:201], v[162:165], v[54:57]
	v_mfma_f32_16x16x32_bf16 v[50:53], v[206:209], v[162:165], v[50:53]
	v_mfma_f32_16x16x32_bf16 v[38:41], v[198:201], v[172:175], v[38:41]
	v_mfma_f32_16x16x32_bf16 v[34:37], v[206:209], v[172:175], v[34:37]
	v_mfma_f32_16x16x32_bf16 v[22:25], v[198:201], v[180:183], v[22:25]
	v_mfma_f32_16x16x32_bf16 v[18:21], v[206:209], v[180:183], v[18:21]
	v_mfma_f32_16x16x32_bf16 v[6:9], v[198:201], v[190:193], v[6:9]
	v_mfma_f32_16x16x32_bf16 v[2:5], v[206:209], v[190:193], v[2:5]
	s_barrier
	s_add_u32 s92, s92, 0x40000
	s_addc_u32 s93, s93, 0
	s_mov_b32 m0, s43
	ds_read_b128 v[158:161], v171 offset:32768
	ds_read_b128 v[162:165], v171 offset:33792
	ds_read_b128 v[166:169], v171 offset:34816
	ds_read_b128 v[172:175], v171 offset:35840
	ds_read_b128 v[176:179], v171 offset:36864
	ds_read_b128 v[180:183], v171 offset:37888
	ds_read_b128 v[184:187], v171 offset:38912
	global_load_lds_dwordx4 v146, s[92:93]
	s_mov_b32 m0, s44
	ds_read_b128 v[190:193], v171 offset:39936
	global_load_lds_dwordx4 v150, s[92:93]
	s_waitcnt lgkmcnt(8)
	s_barrier
	s_waitcnt lgkmcnt(0)
	v_mfma_f32_16x16x32_bf16 v[126:129], v[130:133], v[158:161], v[126:129]
	v_mfma_f32_16x16x32_bf16 v[122:125], v[138:141], v[158:161], v[122:125]
	v_mfma_f32_16x16x32_bf16 v[110:113], v[130:133], v[166:169], v[110:113]
	v_mfma_f32_16x16x32_bf16 v[106:109], v[138:141], v[166:169], v[106:109]
	v_mfma_f32_16x16x32_bf16 v[94:97], v[130:133], v[176:179], v[94:97]
	v_mfma_f32_16x16x32_bf16 v[90:93], v[138:141], v[176:179], v[90:93]
	v_mfma_f32_16x16x32_bf16 v[78:81], v[130:133], v[184:187], v[78:81]
	v_mfma_f32_16x16x32_bf16 v[74:77], v[138:141], v[184:187], v[74:77]
	v_mfma_f32_16x16x32_bf16 v[126:129], v[134:137], v[162:165], v[126:129]
	v_mfma_f32_16x16x32_bf16 v[122:125], v[142:145], v[162:165], v[122:125]
	v_mfma_f32_16x16x32_bf16 v[110:113], v[134:137], v[172:175], v[110:113]
	v_mfma_f32_16x16x32_bf16 v[106:109], v[142:145], v[172:175], v[106:109]
	v_mfma_f32_16x16x32_bf16 v[94:97], v[134:137], v[180:183], v[94:97]
	v_mfma_f32_16x16x32_bf16 v[90:93], v[142:145], v[180:183], v[90:93]
	v_mfma_f32_16x16x32_bf16 v[78:81], v[134:137], v[190:193], v[78:81]
	v_mfma_f32_16x16x32_bf16 v[74:77], v[142:145], v[190:193], v[74:77]
	s_barrier
	s_add_i32 m0, s38, 0x18000
	ds_read_b128 v[194:197], v189 offset:49152
	ds_read_b128 v[198:201], v189 offset:50176
	ds_read_b128 v[202:205], v189 offset:51200
	ds_read_b128 v[206:209], v189 offset:52224
	s_add_u32 s98, s90, s40
	s_addc_u32 s99, s91, s41
	global_load_lds_dwordx4 v148, s[98:99]
	s_add_i32 m0, s38, 0x1a000
	s_nop 0
	global_load_lds_dwordx4 v152, s[98:99]
	s_barrier
	s_waitcnt lgkmcnt(0)
	v_mfma_f32_16x16x32_bf16 v[118:121], v[194:197], v[158:161], v[118:121]
	v_mfma_f32_16x16x32_bf16 v[114:117], v[202:205], v[158:161], v[114:117]
	v_mfma_f32_16x16x32_bf16 v[102:105], v[194:197], v[166:169], v[102:105]
	v_mfma_f32_16x16x32_bf16 v[98:101], v[202:205], v[166:169], v[98:101]
	v_mfma_f32_16x16x32_bf16 v[86:89], v[194:197], v[176:179], v[86:89]
	v_mfma_f32_16x16x32_bf16 v[82:85], v[202:205], v[176:179], v[82:85]
	v_mfma_f32_16x16x32_bf16 v[70:73], v[194:197], v[184:187], v[70:73]
	v_mfma_f32_16x16x32_bf16 v[66:69], v[202:205], v[184:187], v[66:69]
	v_mfma_f32_16x16x32_bf16 v[118:121], v[198:201], v[162:165], v[118:121]
	v_mfma_f32_16x16x32_bf16 v[114:117], v[206:209], v[162:165], v[114:117]
	v_mfma_f32_16x16x32_bf16 v[102:105], v[198:201], v[172:175], v[102:105]
	v_mfma_f32_16x16x32_bf16 v[98:101], v[206:209], v[172:175], v[98:101]
	v_mfma_f32_16x16x32_bf16 v[86:89], v[198:201], v[180:183], v[86:89]
	v_mfma_f32_16x16x32_bf16 v[82:85], v[206:209], v[180:183], v[82:85]
	v_mfma_f32_16x16x32_bf16 v[70:73], v[198:201], v[190:193], v[70:73]
	v_mfma_f32_16x16x32_bf16 v[66:69], v[206:209], v[190:193], v[66:69]
	s_mov_b32 m0, s60
	s_barrier
	ds_read_b128 v[158:161], v171 offset:49152
	ds_read_b128 v[162:165], v171 offset:50176
	ds_read_b128 v[166:169], v171 offset:51200
	ds_read_b128 v[172:175], v171 offset:52224
	ds_read_b128 v[176:179], v171 offset:53248
	ds_read_b128 v[180:183], v171 offset:54272
	ds_read_b128 v[184:187], v171 offset:55296
	ds_read_b128 v[190:193], v171 offset:56320
	s_add_u32 s98, s100, s40
	s_addc_u32 s99, s101, s41
	global_load_lds_dwordx4 v146, s[98:99]
	s_mov_b32 m0, s61
	s_nop 0
	global_load_lds_dwordx4 v150, s[98:99]
	s_waitcnt vmcnt(10)
	s_barrier
	s_waitcnt lgkmcnt(0)
	v_mfma_f32_16x16x32_bf16 v[62:65], v[130:133], v[158:161], v[62:65]
	v_mfma_f32_16x16x32_bf16 v[58:61], v[138:141], v[158:161], v[58:61]
	v_mfma_f32_16x16x32_bf16 v[46:49], v[130:133], v[166:169], v[46:49]
	v_mfma_f32_16x16x32_bf16 v[42:45], v[138:141], v[166:169], v[42:45]
	v_mfma_f32_16x16x32_bf16 v[30:33], v[130:133], v[176:179], v[30:33]
	v_mfma_f32_16x16x32_bf16 v[26:29], v[138:141], v[176:179], v[26:29]
	v_mfma_f32_16x16x32_bf16 v[14:17], v[130:133], v[184:187], v[14:17]
	v_mfma_f32_16x16x32_bf16 v[10:13], v[138:141], v[184:187], v[10:13]
	v_mfma_f32_16x16x32_bf16 v[62:65], v[134:137], v[162:165], v[62:65]
	v_mfma_f32_16x16x32_bf16 v[58:61], v[142:145], v[162:165], v[58:61]
	v_mfma_f32_16x16x32_bf16 v[46:49], v[134:137], v[172:175], v[46:49]
	v_mfma_f32_16x16x32_bf16 v[42:45], v[142:145], v[172:175], v[42:45]
	v_mfma_f32_16x16x32_bf16 v[30:33], v[134:137], v[180:183], v[30:33]
	v_mfma_f32_16x16x32_bf16 v[26:29], v[142:145], v[180:183], v[26:29]
	v_mfma_f32_16x16x32_bf16 v[14:17], v[134:137], v[190:193], v[14:17]
	v_mfma_f32_16x16x32_bf16 v[10:13], v[142:145], v[190:193], v[10:13]
	s_barrier
	s_add_u32 s90, s90, 0x40080
	s_addc_u32 s91, s91, 0
	s_add_i32 m0, s38, 0x1c000
	s_nop 0
	global_load_lds_dwordx4 v148, s[90:91]
	s_add_i32 m0, s38, 0x1e000
	s_nop 0
	global_load_lds_dwordx4 v152, s[90:91]
	ds_read_b128 v[130:133], v189
	ds_read_b128 v[134:137], v189 offset:1024
	ds_read_b128 v[138:141], v189 offset:2048
	ds_read_b128 v[142:145], v189 offset:3072
	s_waitcnt vmcnt(6)
	s_barrier
	v_mfma_f32_16x16x32_bf16 v[54:57], v[194:197], v[158:161], v[54:57]
	v_mfma_f32_16x16x32_bf16 v[50:53], v[202:205], v[158:161], v[50:53]
	v_mfma_f32_16x16x32_bf16 v[38:41], v[194:197], v[166:169], v[38:41]
	v_mfma_f32_16x16x32_bf16 v[34:37], v[202:205], v[166:169], v[34:37]
	v_mfma_f32_16x16x32_bf16 v[22:25], v[194:197], v[176:179], v[22:25]
	v_mfma_f32_16x16x32_bf16 v[18:21], v[202:205], v[176:179], v[18:21]
	v_mfma_f32_16x16x32_bf16 v[6:9], v[194:197], v[184:187], v[6:9]
	v_mfma_f32_16x16x32_bf16 v[2:5], v[202:205], v[184:187], v[2:5]
	v_mfma_f32_16x16x32_bf16 v[54:57], v[198:201], v[162:165], v[54:57]
	v_mfma_f32_16x16x32_bf16 v[50:53], v[206:209], v[162:165], v[50:53]
	v_mfma_f32_16x16x32_bf16 v[38:41], v[198:201], v[172:175], v[38:41]
	v_mfma_f32_16x16x32_bf16 v[34:37], v[206:209], v[172:175], v[34:37]
	v_mfma_f32_16x16x32_bf16 v[22:25], v[198:201], v[180:183], v[22:25]
	v_mfma_f32_16x16x32_bf16 v[18:21], v[206:209], v[180:183], v[18:21]
	v_mfma_f32_16x16x32_bf16 v[6:9], v[198:201], v[190:193], v[6:9]
	v_mfma_f32_16x16x32_bf16 v[2:5], v[206:209], v[190:193], v[2:5]
	s_add_i32 s85, s85, 2
	s_add_u32 s88, s88, 0x100
	s_addc_u32 s89, s89, 0
	s_add_u32 s34, s34, 0x100
	s_addc_u32 s79, s79, 0
	s_add_u32 s87, s88, 0xfffc0080
	s_addc_u32 s90, s89, -1
	s_cmp_eq_u32 s85, 12
	s_cselect_b32 s93, s13, s90
	s_cselect_b32 s92, s22, s87
	s_cselect_b32 s91, s7, s79
	s_cselect_b32 s90, s23, s34
	s_cmp_gt_u32 s85, 13
	s_cbranch_scc0 .LBB0_1209
	s_barrier
	s_waitcnt lgkmcnt(0)
	v_mov_b32_e32 v131, v252
	s_lshl_b32 s7, s86, 8
	v_and_b32_e32 v130, 63, v131
	v_or_b32_e32 v0, s72, v130
	v_lshrrev_b32_e32 v0, 1, v0
	v_and_or_b32 v132, v0, 63, s73
	v_add_u32_e32 v134, s7, v132
	v_ashrrev_i32_e32 v135, 31, v134
	v_and_b32_e32 v142, 1, v131
	v_lshlrev_b64 v[134:135], 6, v[134:135]
	v_lshl_add_u64 v[134:135], s[82:83], 0, v[134:135]
	v_lshlrev_b32_e32 v0, 5, v142
	v_lshl_add_u64 v[138:139], v[134:135], 0, v[0:1]
	global_load_dwordx4 v[134:137], v[138:139], off
	s_nop 0
	global_load_dwordx4 v[138:141], v[138:139], off offset:16
	v_lshlrev_b32_e32 v0, 2, v130
	v_cmp_eq_u32_e32 vcc, 0, v142
	s_waitcnt vmcnt(0)
	v_add_f32_e32 v133, v134, v135
	v_add_f32_e32 v134, v136, v137
	v_add_f32_e32 v135, v138, v139
	v_add_f32_e32 v136, v140, v141
	v_add_f32_e32 v133, v133, v134
	v_add_f32_e32 v134, v135, v136
	v_add_f32_e32 v133, v133, v134
	v_xor_b32_e32 v134, 4, v0
	ds_bpermute_b32 v134, v134, v133
	s_and_saveexec_b64 s[22:23], vcc
	s_cbranch_execz .LBB0_1212
	s_waitcnt lgkmcnt(0)
	v_add_f32_e32 v133, v133, v134
	v_fmamk_f32 v133, v133, 0x3a800000, v224
	s_mov_b32 s13, 0x800000
	v_mul_f32_e32 v134, 0x4b800000, v133
	v_cmp_gt_f32_e32 vcc, s13, v133
	v_lshl_add_u32 v132, v132, 2, 0
	v_add_u32_e32 v132, 0x20000, v132
	v_cndmask_b32_e32 v133, v133, v134, vcc
	v_rsq_f32_e32 v133, v133
	s_nop 0
	v_mul_f32_e32 v134, 0x45800000, v133
	v_cndmask_b32_e32 v133, v133, v134, vcc
	ds_write_b32 v132, v133
